# EpiZ: third tap load issued before the row-scale wait in 6 steps (counted wait 3 instead of 2/0)
# baseline (speedup 1.0000x reference)
; __device__ __forceinline__ u32x4 pack8(f32x4 a, f32x4 b) { u32x4 w; w.x = cvt_pk_bf16(a[0], a[1]); w.y = cvt_pk_bf16(a[2], a[3]); w.z = cvt_pk_bf16(b[0], b[1]); w.w = cvt_pk_bf16(b[2], b[3]); return w; }
; __device__ __forceinline__ float rs_of(const float* ss, int row) { return 1.0f / sqrtf(ss[row] * (1.0f / 2048.0f) + 1e-5f); }
;     __device__ __forceinline__ void operator()(const f32x4 (&acc)[2][2][4][2], const Unit& u, int wr, int wc, int fr, int fq) const {
;     ...
;                     const int row = row0 + ai * HALF + m * 16, s = row & 8191; const float rr = rs_of(ss, row);
;                     const size_t off = (size_t)row * 2048 + ch0;
;                     f32x4 c0a, c0b, p1a, p1b, p2a, p2b;
;                     unpk(*(const u32x4*)(V + off), c0a, c0b);
;                     if (s >= 2) { unpk(*(const u32x4*)(V + off - 2048), p1a, p1b); unpk(*(const u32x4*)(V + off - 4096), p2a, p2b); }
;                     else if (s == 1) { unpk(*(const u32x4*)(V + off - 2048), p1a, p1b); p2a = *(const f32x4*)(Vm + 15 * 2048 + ch0); p2b = *(const f32x4*)(Vm + 15 * 2048 + ch0 + 4); }
;                     else { p1a = *(const f32x4*)(Vm + 15 * 2048 + ch0); p1b = *(const f32x4*)(Vm + 15 * 2048 + ch0 + 4); p2a = *(const f32x4*)(Vm + 14 * 2048 + ch0); p2b = *(const f32x4*)(Vm + 14 * 2048 + ch0 + 4); }
;                     const f32x4 za = (acc[ai][bj][m][0] * rr) * (w0a * p2a + w1a * p1a + w2a * c0a);
;                     const f32x4 zb = (acc[ai][bj][m][1] * rr) * (w0b * p2b + w1b * p1b + w2b * c0b);
;                     *(u32x4*)(Z + off) = pack8(za, zb);
;                     if (m & 1) asm volatile("" ::: "memory");
.LBB0_514:
	s_or_b64 exec, exec, s[0:1]
	s_waitcnt vmcnt(0)
	v_fmamk_f32 v178, v217, 0x3a000000, v205
	v_mul_f32_e32 v179, 0x4f800000, v178
	v_cmp_gt_f32_e32 vcc, s83, v178
	v_pk_mul_f32 v[162:163], v[106:107], v[162:163]
	v_pk_mul_f32 v[160:161], v[104:105], v[160:161]
	v_cndmask_b32_e32 v178, v178, v179, vcc
	v_sqrt_f32_e32 v179, v178
	v_pk_fma_f32 v[162:163], v[110:111], v[170:171], v[162:163]
	v_pk_mul_f32 v[156:157], v[92:93], v[156:157]
	v_pk_fma_f32 v[160:161], v[108:109], v[168:169], v[160:161]
	v_add_u32_e32 v180, -1, v179
	v_fma_f32 v202, -v180, v179, v178
	v_add_u32_e32 v181, 1, v179
	v_cmp_ge_f32_e64 s[0:1], 0, v202
	v_pk_fma_f32 v[156:157], v[96:97], v[164:165], v[156:157]
	s_movk_i32 s6, 0xe000
	v_cndmask_b32_e64 v180, v179, v180, s[0:1]
	v_fma_f32 v179, -v181, v179, v178
	v_cmp_lt_f32_e64 s[0:1], 0, v179
	s_movk_i32 s25, 0xe000
	s_nop 0
	v_cndmask_b32_e64 v179, v180, v181, s[0:1]
	v_mul_f32_e32 v180, 0x37800000, v179
	v_cndmask_b32_e32 v179, v179, v180, vcc
	v_cmp_class_f32_e32 vcc, v178, v206
	s_nop 1
	v_cndmask_b32_e32 v178, v179, v178, vcc
	v_div_scale_f32 v179, s[0:1], v178, v178, 1.0
	v_rcp_f32_e32 v180, v179
	s_nop 0
	v_fma_f32 v181, -v179, v180, 1.0
	v_fmac_f32_e32 v180, v181, v180
	v_div_scale_f32 v181, vcc, 1.0, v178, 1.0
	v_mul_f32_e32 v202, v181, v180
	v_fma_f32 v203, -v179, v202, v181
	v_fmac_f32_e32 v202, v203, v180
	v_fma_f32 v179, -v179, v202, v181
	v_div_fmas_f32 v179, v179, v180, v202
	v_div_fixup_f32 v178, v179, v178, 1.0
	v_lshlrev_b32_e32 v180, 16, v152
	v_and_b32_e32 v181, 0xffff0000, v152
	v_lshlrev_b32_e32 v152, 16, v153
	v_and_b32_e32 v153, 0xffff0000, v153
	v_pk_mul_f32 v[150:151], v[150:151], v[178:179] op_sel_hi:[1,0]
	v_pk_fma_f32 v[152:153], v[102:103], v[152:153], v[162:163]
	v_lshlrev_b32_e32 v202, 16, v154
	v_pk_mul_f32 v[150:151], v[150:151], v[152:153]
	v_pk_mul_f32 v[152:153], v[94:95], v[158:159]
	v_and_b32_e32 v203, 0xffff0000, v154
	v_lshlrev_b32_e32 v154, 16, v155
	v_and_b32_e32 v155, 0xffff0000, v155
	v_pk_fma_f32 v[152:153], v[98:99], v[166:167], v[152:153]
	v_pk_mul_f32 v[148:149], v[148:149], v[178:179] op_sel_hi:[1,0]
	v_pk_fma_f32 v[160:161], v[100:101], v[180:181], v[160:161]
	v_pk_mul_f32 v[144:145], v[144:145], v[178:179] op_sel_hi:[1,0]
	v_pk_mul_f32 v[146:147], v[146:147], v[178:179] op_sel_hi:[1,0]
	v_pk_fma_f32 v[156:157], v[88:89], v[202:203], v[156:157]
	v_pk_fma_f32 v[152:153], v[90:91], v[154:155], v[152:153]
	v_pk_mul_f32 v[148:149], v[148:149], v[160:161]
	v_pk_mul_f32 v[152:153], v[146:147], v[152:153]
	v_pk_mul_f32 v[146:147], v[144:145], v[156:157]
	v_cvt_pk_bf16_f32 v144, v148, v149
	v_cvt_pk_bf16_f32 v145, v150, v151
	v_lshl_add_u64 v[148:149], v[200:201], 1, s[14:15]
	v_cvt_pk_bf16_f32 v146, v146, v147
	v_cvt_pk_bf16_f32 v147, v152, v153
	global_store_dwordx4 v[148:149], v[144:147], off
	s_nop 1
	v_or_b32_e32 v146, 16, v196
	v_ashrrev_i32_e32 v147, 31, v146
	v_lshl_add_u64 v[144:145], v[146:147], 2, s[16:17]
	v_lshlrev_b64 v[146:147], 11, v[146:147]
	v_lshl_add_u64 v[148:149], v[146:147], 0, v[192:193]
	v_lshlrev_b64 v[160:161], 1, v[148:149]
	v_lshl_add_u64 v[156:157], s[12:13], 0, v[160:161]
	global_load_dword v162, v[144:145], off
	global_load_dwordx4 v[148:151], v[156:157], off
	global_load_dwordx4 v[152:155], v[156:157], off offset:-4096
	v_add_co_u32_e32 v156, vcc, s6, v156
	s_nop 1
	v_addc_co_u32_e32 v157, vcc, -1, v157, vcc
	global_load_dwordx4 v[156:159], v[156:157], off
	s_waitcnt vmcnt(3)
	v_fmamk_f32 v180, v162, 0x3a000000, v205
	v_cmp_gt_f32_e32 vcc, s83, v180
	s_waitcnt vmcnt(1)
	v_lshlrev_b32_e32 v166, 16, v152
	v_and_b32_e32 v167, 0xffff0000, v152
	v_lshlrev_b32_e32 v152, 16, v153
	v_and_b32_e32 v153, 0xffff0000, v153
	v_lshlrev_b32_e32 v162, 16, v148
	v_and_b32_e32 v163, 0xffff0000, v148
	v_lshlrev_b32_e32 v148, 16, v149
	v_and_b32_e32 v149, 0xffff0000, v149
	v_lshlrev_b32_e32 v168, 16, v154
	v_and_b32_e32 v169, 0xffff0000, v154
	v_lshlrev_b32_e32 v154, 16, v155
	v_and_b32_e32 v155, 0xffff0000, v155
	v_lshlrev_b32_e32 v164, 16, v150
	v_and_b32_e32 v165, 0xffff0000, v150
	v_lshlrev_b32_e32 v150, 16, v151
	v_and_b32_e32 v151, 0xffff0000, v151
	s_waitcnt vmcnt(0)
	v_lshlrev_b32_e32 v178, 16, v158
	v_and_b32_e32 v179, 0xffff0000, v158
	v_mul_f32_e32 v158, 0x4f800000, v180
	v_cndmask_b32_e32 v180, v180, v158, vcc
	v_sqrt_f32_e32 v181, v180
	v_lshlrev_b32_e32 v170, 16, v156
	v_and_b32_e32 v171, 0xffff0000, v156
	v_lshlrev_b32_e32 v156, 16, v157
	v_add_u32_e32 v200, -1, v181
	v_add_u32_e32 v201, 1, v181
	v_fma_f32 v202, -v200, v181, v180
	v_fma_f32 v203, -v201, v181, v180
	v_cmp_ge_f32_e64 s[0:1], 0, v202
	v_and_b32_e32 v157, 0xffff0000, v157
	v_pk_mul_f32 v[156:157], v[110:111], v[156:157]
	v_cndmask_b32_e64 v181, v181, v200, s[0:1]
	v_cmp_lt_f32_e64 s[0:1], 0, v203
	v_pk_fma_f32 v[152:153], v[106:107], v[152:153], v[156:157]
	v_lshlrev_b32_e32 v158, 16, v159
	v_cndmask_b32_e64 v181, v181, v201, s[0:1]
	v_mul_f32_e32 v200, 0x37800000, v181
	v_cndmask_b32_e32 v181, v181, v200, vcc
	v_cmp_class_f32_e32 vcc, v180, v206
	v_and_b32_e32 v159, 0xffff0000, v159
	v_pk_mul_f32 v[170:171], v[108:109], v[170:171]
	v_cndmask_b32_e32 v180, v181, v180, vcc
	v_div_scale_f32 v181, s[0:1], v180, v180, 1.0
	v_rcp_f32_e32 v200, v181
	v_div_scale_f32 v201, vcc, 1.0, v180, 1.0
	v_pk_fma_f32 v[148:149], v[102:103], v[148:149], v[152:153]
	v_fma_f32 v202, -v181, v200, 1.0
	v_fmac_f32_e32 v200, v202, v200
	v_mul_f32_e32 v202, v201, v200
	v_fma_f32 v203, -v181, v202, v201
	v_fmac_f32_e32 v202, v203, v200
	v_fma_f32 v181, -v181, v202, v201
	v_div_fmas_f32 v181, v181, v200, v202
	v_div_fixup_f32 v180, v181, v180, 1.0
	v_pk_mul_f32 v[142:143], v[142:143], v[180:181] op_sel_hi:[1,0]
; __device__ __forceinline__ u32x4 pack8(f32x4 a, f32x4 b) { u32x4 w; w.x = cvt_pk_bf16(a[0], a[1]); w.y = cvt_pk_bf16(a[2], a[3]); w.z = cvt_pk_bf16(b[0], b[1]); w.w = cvt_pk_bf16(b[2], b[3]); return w; }
; __device__ __forceinline__ float rs_of(const float* ss, int row) { return 1.0f / sqrtf(ss[row] * (1.0f / 2048.0f) + 1e-5f); }
;     __device__ __forceinline__ void operator()(const f32x4 (&acc)[2][2][4][2], const Unit& u, int wr, int wc, int fr, int fq) const {
;     ...
;                     const int row = row0 + ai * HALF + m * 16, s = row & 8191; const float rr = rs_of(ss, row);
;                     const size_t off = (size_t)row * 2048 + ch0;
;                     f32x4 c0a, c0b, p1a, p1b, p2a, p2b;
;                     unpk(*(const u32x4*)(V + off), c0a, c0b);
;                     if (s >= 2) { unpk(*(const u32x4*)(V + off - 2048), p1a, p1b); unpk(*(const u32x4*)(V + off - 4096), p2a, p2b); }
;                     else if (s == 1) { unpk(*(const u32x4*)(V + off - 2048), p1a, p1b); p2a = *(const f32x4*)(Vm + 15 * 2048 + ch0); p2b = *(const f32x4*)(Vm + 15 * 2048 + ch0 + 4); }
;                     else { p1a = *(const f32x4*)(Vm + 15 * 2048 + ch0); p1b = *(const f32x4*)(Vm + 15 * 2048 + ch0 + 4); p2a = *(const f32x4*)(Vm + 14 * 2048 + ch0); p2b = *(const f32x4*)(Vm + 14 * 2048 + ch0 + 4); }
;                     const f32x4 za = (acc[ai][bj][m][0] * rr) * (w0a * p2a + w1a * p1a + w2a * c0a);
;                     const f32x4 zb = (acc[ai][bj][m][1] * rr) * (w0b * p2b + w1b * p1b + w2b * c0b);
;                     *(u32x4*)(Z + off) = pack8(za, zb);
;                     if (m & 1) asm volatile("" ::: "memory");
	v_pk_fma_f32 v[156:157], v[104:105], v[166:167], v[170:171]
	v_pk_mul_f32 v[142:143], v[142:143], v[148:149]
	v_pk_mul_f32 v[148:149], v[96:97], v[178:179]
	v_pk_mul_f32 v[152:153], v[98:99], v[158:159]
	v_pk_mul_f32 v[140:141], v[140:141], v[180:181] op_sel_hi:[1,0]
	v_pk_fma_f32 v[156:157], v[100:101], v[162:163], v[156:157]
	v_pk_fma_f32 v[152:153], v[94:95], v[154:155], v[152:153]
	v_pk_fma_f32 v[148:149], v[92:93], v[168:169], v[148:149]
	v_pk_mul_f32 v[140:141], v[140:141], v[156:157]
	v_pk_mul_f32 v[136:137], v[136:137], v[180:181] op_sel_hi:[1,0]
	v_pk_mul_f32 v[138:139], v[138:139], v[180:181] op_sel_hi:[1,0]
	v_pk_fma_f32 v[148:149], v[88:89], v[164:165], v[148:149]
	v_pk_fma_f32 v[150:151], v[90:91], v[150:151], v[152:153]
	s_nop 0
	v_pk_mul_f32 v[150:151], v[138:139], v[150:151]
	v_pk_mul_f32 v[138:139], v[136:137], v[148:149]
	v_cvt_pk_bf16_f32 v136, v140, v141
	v_lshl_add_u64 v[140:141], s[14:15], 0, v[160:161]
	v_cvt_pk_bf16_f32 v137, v142, v143
	v_cvt_pk_bf16_f32 v138, v138, v139
	v_cvt_pk_bf16_f32 v139, v150, v151
	global_store_dwordx4 v[140:141], v[136:139], off
	s_nop 1
	v_or_b32_e32 v136, 32, v196
	v_ashrrev_i32_e32 v137, 31, v136
	v_lshlrev_b64 v[150:151], 11, v[136:137]
	v_lshl_add_u64 v[148:149], v[136:137], 2, s[16:17]
	v_lshl_add_u64 v[136:137], v[150:151], 0, v[192:193]
	v_lshlrev_b64 v[156:157], 1, v[136:137]
	v_lshl_add_u64 v[152:153], s[12:13], 0, v[156:157]
	global_load_dword v158, v[148:149], off
	global_load_dwordx4 v[136:139], v[152:153], off
	global_load_dwordx4 v[140:143], v[152:153], off offset:-4096
	v_add_co_u32_e32 v152, vcc, s6, v152
	s_nop 1
	v_addc_co_u32_e32 v153, vcc, -1, v153, vcc
	global_load_dwordx4 v[152:155], v[152:153], off
	s_waitcnt vmcnt(3)
	v_fmamk_f32 v170, v158, 0x3a000000, v205
	v_mul_f32_e32 v171, 0x4f800000, v170
	v_cmp_gt_f32_e32 vcc, s83, v170
	s_waitcnt vmcnt(1)
	v_lshlrev_b32_e32 v162, 16, v140
	v_and_b32_e32 v163, 0xffff0000, v140
	v_lshlrev_b32_e32 v140, 16, v141
	v_and_b32_e32 v141, 0xffff0000, v141
	v_cndmask_b32_e32 v170, v170, v171, vcc
	v_lshlrev_b32_e32 v164, 16, v142
	v_and_b32_e32 v165, 0xffff0000, v142
	v_lshlrev_b32_e32 v142, 16, v143
	v_and_b32_e32 v143, 0xffff0000, v143
	v_lshlrev_b32_e32 v158, 16, v136
	v_and_b32_e32 v159, 0xffff0000, v136
	v_lshlrev_b32_e32 v136, 16, v137
	v_and_b32_e32 v137, 0xffff0000, v137
	v_lshlrev_b32_e32 v160, 16, v138
	v_and_b32_e32 v161, 0xffff0000, v138
	v_lshlrev_b32_e32 v138, 16, v139
	v_and_b32_e32 v139, 0xffff0000, v139
	s_waitcnt vmcnt(0)
	v_lshlrev_b32_e32 v166, 16, v152
	v_and_b32_e32 v167, 0xffff0000, v152
	v_lshlrev_b32_e32 v152, 16, v153
	v_and_b32_e32 v153, 0xffff0000, v153
	v_pk_mul_f32 v[166:167], v[108:109], v[166:167]
	v_pk_mul_f32 v[152:153], v[110:111], v[152:153]
	v_lshlrev_b32_e32 v168, 16, v154
	v_pk_fma_f32 v[140:141], v[106:107], v[140:141], v[152:153]
	v_pk_fma_f32 v[152:153], v[104:105], v[162:163], v[166:167]
	v_sqrt_f32_e32 v162, v170
	v_and_b32_e32 v169, 0xffff0000, v154
	v_lshlrev_b32_e32 v154, 16, v155
	v_and_b32_e32 v155, 0xffff0000, v155
	v_pk_mul_f32 v[168:169], v[96:97], v[168:169]
	v_pk_mul_f32 v[154:155], v[98:99], v[154:155]
	v_pk_fma_f32 v[136:137], v[102:103], v[136:137], v[140:141]
	v_pk_fma_f32 v[142:143], v[94:95], v[142:143], v[154:155]
	v_pk_fma_f32 v[154:155], v[92:93], v[164:165], v[168:169]
	v_pk_fma_f32 v[152:153], v[100:101], v[158:159], v[152:153]
	v_pk_fma_f32 v[140:141], v[88:89], v[160:161], v[154:155]
	v_add_u32_e32 v154, -1, v162
	v_add_u32_e32 v155, 1, v162
	v_fma_f32 v158, -v154, v162, v170
	v_fma_f32 v159, -v155, v162, v170
	v_cmp_ge_f32_e64 s[0:1], 0, v158
	v_pk_fma_f32 v[138:139], v[90:91], v[138:139], v[142:143]
	v_add_u32_e32 v160, 0x80, v196
	v_cndmask_b32_e64 v154, v162, v154, s[0:1]
	v_cmp_lt_f32_e64 s[0:1], 0, v159
	v_ashrrev_i32_e32 v161, 31, v160
	s_nop 0
	v_cndmask_b32_e64 v154, v154, v155, s[0:1]
	v_mul_f32_e32 v155, 0x37800000, v154
	v_cndmask_b32_e32 v154, v154, v155, vcc
	v_cmp_class_f32_e32 vcc, v170, v206
	s_nop 1
	v_cndmask_b32_e32 v154, v154, v170, vcc
	v_div_scale_f32 v155, s[0:1], v154, v154, 1.0
	v_rcp_f32_e32 v158, v155
	v_div_scale_f32 v142, vcc, 1.0, v154, 1.0
	v_fma_f32 v143, -v155, v158, 1.0
	v_fmac_f32_e32 v158, v143, v158
	v_mul_f32_e32 v143, v142, v158
	v_fma_f32 v159, -v155, v143, v142
	v_fmac_f32_e32 v143, v159, v158
	v_fma_f32 v142, -v155, v143, v142
	v_div_fmas_f32 v142, v142, v158, v143
	v_div_fixup_f32 v142, v142, v154, 1.0
	v_pk_mul_f32 v[132:133], v[132:133], v[142:143] op_sel_hi:[1,0]
	v_pk_mul_f32 v[134:135], v[134:135], v[142:143] op_sel_hi:[1,0]
	v_pk_mul_f32 v[128:129], v[128:129], v[142:143] op_sel_hi:[1,0]
	v_pk_mul_f32 v[130:131], v[130:131], v[142:143] op_sel_hi:[1,0]
	v_pk_mul_f32 v[132:133], v[132:133], v[152:153]
	v_pk_mul_f32 v[134:135], v[134:135], v[136:137]
	v_pk_mul_f32 v[136:137], v[130:131], v[138:139]
	v_pk_mul_f32 v[130:131], v[128:129], v[140:141]
	v_cvt_pk_bf16_f32 v128, v132, v133
	v_lshl_add_u64 v[132:133], s[14:15], 0, v[156:157]
	v_cvt_pk_bf16_f32 v129, v134, v135
	v_cvt_pk_bf16_f32 v130, v130, v131
	v_cvt_pk_bf16_f32 v131, v136, v137
	global_store_dwordx4 v[132:133], v[128:131], off
	v_lshlrev_b64 v[142:143], 11, v[160:161]
	v_lshl_add_u64 v[154:155], v[142:143], 0, v[192:193]
	v_or_b32_e32 v128, 48, v196
	v_ashrrev_i32_e32 v129, 31, v128
	v_lshlrev_b64 v[152:153], 11, v[128:129]
	v_lshl_add_u64 v[140:141], v[128:129], 2, s[16:17]
	v_lshl_add_u64 v[128:129], v[152:153], 0, v[192:193]
	v_lshlrev_b64 v[158:159], 1, v[128:129]
	v_lshl_add_u64 v[136:137], s[12:13], 0, v[158:159]
	global_load_dword v162, v[140:141], off
	global_load_dwordx4 v[128:131], v[136:137], off
	global_load_dwordx4 v[132:135], v[136:137], off offset:-4096
	v_add_co_u32_e32 v136, vcc, s6, v136
	v_lshl_add_u64 v[158:159], s[14:15], 0, v[158:159]
	s_nop 0
	v_addc_co_u32_e32 v137, vcc, -1, v137, vcc
	global_load_dwordx4 v[136:139], v[136:137], off
	v_lshl_add_u64 v[156:157], v[154:155], 1, s[12:13]
	s_waitcnt vmcnt(3)
; __device__ __forceinline__ float rs_of(const float* ss, int row) { return 1.0f / sqrtf(ss[row] * (1.0f / 2048.0f) + 1e-5f); }
;     __device__ __forceinline__ void operator()(const f32x4 (&acc)[2][2][4][2], const Unit& u, int wr, int wc, int fr, int fq) const {
;     ...
;                     const int row = row0 + ai * HALF + m * 16, s = row & 8191; const float rr = rs_of(ss, row);
;                     const size_t off = (size_t)row * 2048 + ch0;
;                     f32x4 c0a, c0b, p1a, p1b, p2a, p2b;
;                     unpk(*(const u32x4*)(V + off), c0a, c0b);
;                     if (s >= 2) { unpk(*(const u32x4*)(V + off - 2048), p1a, p1b); unpk(*(const u32x4*)(V + off - 4096), p2a, p2b); }
;                     else if (s == 1) { unpk(*(const u32x4*)(V + off - 2048), p1a, p1b); p2a = *(const f32x4*)(Vm + 15 * 2048 + ch0); p2b = *(const f32x4*)(Vm + 15 * 2048 + ch0 + 4); }
;                     else { p1a = *(const f32x4*)(Vm + 15 * 2048 + ch0); p1b = *(const f32x4*)(Vm + 15 * 2048 + ch0 + 4); p2a = *(const f32x4*)(Vm + 14 * 2048 + ch0); p2b = *(const f32x4*)(Vm + 14 * 2048 + ch0 + 4); }
	v_fmamk_f32 v161, v162, 0x3a000000, v205
	v_mul_f32_e32 v180, 0x4f800000, v161
	v_cmp_gt_f32_e32 vcc, s83, v161
	s_waitcnt vmcnt(1)
	v_lshlrev_b32_e32 v166, 16, v132
	v_and_b32_e32 v167, 0xffff0000, v132
	v_lshlrev_b32_e32 v132, 16, v133
	v_and_b32_e32 v133, 0xffff0000, v133
	s_waitcnt vmcnt(0)
	v_lshlrev_b32_e32 v170, 16, v136
	v_and_b32_e32 v171, 0xffff0000, v136
	v_lshlrev_b32_e32 v136, 16, v137
	v_and_b32_e32 v137, 0xffff0000, v137
	v_pk_mul_f32 v[170:171], v[108:109], v[170:171]
	v_pk_mul_f32 v[136:137], v[110:111], v[136:137]
	v_cndmask_b32_e32 v161, v161, v180, vcc
	v_pk_fma_f32 v[132:133], v[106:107], v[132:133], v[136:137]
	v_pk_fma_f32 v[136:137], v[104:105], v[166:167], v[170:171]
	v_sqrt_f32_e32 v166, v161
	v_lshlrev_b32_e32 v178, 16, v138
	v_and_b32_e32 v179, 0xffff0000, v138
	v_lshlrev_b32_e32 v138, 16, v139
	v_and_b32_e32 v139, 0xffff0000, v139
	v_lshlrev_b32_e32 v168, 16, v134
	v_and_b32_e32 v169, 0xffff0000, v134
	v_lshlrev_b32_e32 v134, 16, v135
	v_and_b32_e32 v135, 0xffff0000, v135
	v_pk_mul_f32 v[178:179], v[96:97], v[178:179]
	v_pk_mul_f32 v[138:139], v[98:99], v[138:139]
	v_lshlrev_b32_e32 v162, 16, v128
	v_and_b32_e32 v163, 0xffff0000, v128
	v_lshlrev_b32_e32 v128, 16, v129
	v_and_b32_e32 v129, 0xffff0000, v129
	v_lshlrev_b32_e32 v164, 16, v130
	v_and_b32_e32 v165, 0xffff0000, v130
	v_pk_fma_f32 v[134:135], v[94:95], v[134:135], v[138:139]
	v_pk_fma_f32 v[138:139], v[92:93], v[168:169], v[178:179]
	v_pk_fma_f32 v[128:129], v[102:103], v[128:129], v[132:133]
	v_pk_fma_f32 v[132:133], v[88:89], v[164:165], v[138:139]
	v_add_u32_e32 v138, -1, v166
	v_pk_fma_f32 v[136:137], v[100:101], v[162:163], v[136:137]
	v_add_u32_e32 v139, 1, v166
	v_fma_f32 v162, -v138, v166, v161
	v_fma_f32 v163, -v139, v166, v161
	v_cmp_ge_f32_e64 s[0:1], 0, v162
	v_lshlrev_b32_e32 v130, 16, v131
	v_and_b32_e32 v131, 0xffff0000, v131
	v_cndmask_b32_e64 v138, v166, v138, s[0:1]
	v_cmp_lt_f32_e64 s[0:1], 0, v163
	v_pk_fma_f32 v[130:131], v[90:91], v[130:131], v[134:135]
	s_nop 0
	v_cndmask_b32_e64 v138, v138, v139, s[0:1]
	v_mul_f32_e32 v139, 0x37800000, v138
	v_cndmask_b32_e32 v138, v138, v139, vcc
	v_cmp_class_f32_e32 vcc, v161, v206
	s_nop 1
	v_cndmask_b32_e32 v138, v138, v161, vcc
	v_div_scale_f32 v139, s[0:1], v138, v138, 1.0
	v_rcp_f32_e32 v161, v139
	v_div_scale_f32 v134, vcc, 1.0, v138, 1.0
	v_fma_f32 v135, -v139, v161, 1.0
	v_fmac_f32_e32 v161, v135, v161
	v_mul_f32_e32 v135, v134, v161
	v_fma_f32 v162, -v139, v135, v134
	v_fmac_f32_e32 v135, v162, v161
	v_fma_f32 v134, -v139, v135, v134
	v_div_fmas_f32 v134, v134, v161, v135
	v_div_fixup_f32 v134, v134, v138, 1.0
	v_pk_mul_f32 v[126:127], v[126:127], v[134:135] op_sel_hi:[1,0]
	v_pk_mul_f32 v[120:121], v[120:121], v[134:135] op_sel_hi:[1,0]
	v_pk_mul_f32 v[122:123], v[122:123], v[134:135] op_sel_hi:[1,0]
	v_pk_mul_f32 v[124:125], v[124:125], v[134:135] op_sel_hi:[1,0]
	v_pk_mul_f32 v[126:127], v[126:127], v[128:129]
	v_pk_mul_f32 v[128:129], v[122:123], v[130:131]
	v_pk_mul_f32 v[122:123], v[120:121], v[132:133]
	v_pk_mul_f32 v[124:125], v[124:125], v[136:137]
	s_nop 0
	v_cvt_pk_bf16_f32 v120, v124, v125
	v_cvt_pk_bf16_f32 v121, v126, v127
	v_cvt_pk_bf16_f32 v122, v122, v123
	v_cvt_pk_bf16_f32 v123, v128, v129
	global_store_dwordx4 v[158:159], v[120:123], off
	global_load_dword v159, v[188:189], off offset:512
	global_load_dwordx4 v[120:123], v[156:157], off
	v_and_b32_e32 v158, 0x1fcf, v160
	v_cmp_gt_u32_e64 s[6:7], 2, v158
	s_and_saveexec_b64 s[0:1], s[6:7]
	s_xor_b64 s[0:1], exec, s[0:1]
	s_cbranch_execz .LBB0_520
	v_cmp_ne_u32_e32 vcc, 1, v158
	s_and_saveexec_b64 s[36:37], vcc
	s_xor_b64 s[36:37], exec, s[36:37]
	s_cbranch_execz .LBB0_517
	v_lshl_add_u64 v[128:129], s[20:21], 0, v[198:199]
	v_lshl_add_u64 v[136:137], s[22:23], 0, v[198:199]
	global_load_dwordx4 v[124:127], v[128:129], off offset:16
	s_nop 0
	global_load_dwordx4 v[128:131], v[128:129], off
	s_nop 0
	global_load_dwordx4 v[132:135], v[136:137], off offset:16
	s_nop 0
	global_load_dwordx4 v[136:139], v[136:137], off

; __device__ __forceinline__ u32x4 pack8(f32x4 a, f32x4 b) { u32x4 w; w.x = cvt_pk_bf16(a[0], a[1]); w.y = cvt_pk_bf16(a[2], a[3]); w.z = cvt_pk_bf16(b[0], b[1]); w.w = cvt_pk_bf16(b[2], b[3]); return w; }
; __device__ __forceinline__ float rs_of(const float* ss, int row) { return 1.0f / sqrtf(ss[row] * (1.0f / 2048.0f) + 1e-5f); }
;     __device__ __forceinline__ void operator()(const f32x4 (&acc)[2][2][4][2], const Unit& u, int wr, int wc, int fr, int fq) const {
;     ...
;                     const int row = row0 + ai * HALF + m * 16, s = row & 8191; const float rr = rs_of(ss, row);
;                     const size_t off = (size_t)row * 2048 + ch0;
;                     f32x4 c0a, c0b, p1a, p1b, p2a, p2b;
;                     unpk(*(const u32x4*)(V + off), c0a, c0b);
;                     if (s >= 2) { unpk(*(const u32x4*)(V + off - 2048), p1a, p1b); unpk(*(const u32x4*)(V + off - 4096), p2a, p2b); }
;                     else if (s == 1) { unpk(*(const u32x4*)(V + off - 2048), p1a, p1b); p2a = *(const f32x4*)(Vm + 15 * 2048 + ch0); p2b = *(const f32x4*)(Vm + 15 * 2048 + ch0 + 4); }
;                     else { p1a = *(const f32x4*)(Vm + 15 * 2048 + ch0); p1b = *(const f32x4*)(Vm + 15 * 2048 + ch0 + 4); p2a = *(const f32x4*)(Vm + 14 * 2048 + ch0); p2b = *(const f32x4*)(Vm + 14 * 2048 + ch0 + 4); }
;                     const f32x4 za = (acc[ai][bj][m][0] * rr) * (w0a * p2a + w1a * p1a + w2a * c0a);
;                     const f32x4 zb = (acc[ai][bj][m][1] * rr) * (w0b * p2b + w1b * p1b + w2b * c0b);
;                     *(u32x4*)(Z + off) = pack8(za, zb);
;                     if (m & 1) asm volatile("" ::: "memory");
.LBB0_522:
	s_or_b64 exec, exec, s[0:1]
	s_waitcnt vmcnt(1)
	v_fmamk_f32 v156, v159, 0x3a000000, v205
	v_mul_f32_e32 v157, 0x4f800000, v156
	v_cmp_gt_f32_e32 vcc, s83, v156
	v_pk_mul_f32 v[130:131], v[106:107], v[130:131]
	v_pk_mul_f32 v[128:129], v[104:105], v[128:129]
	v_cndmask_b32_e32 v156, v156, v157, vcc
	v_sqrt_f32_e32 v157, v156
	s_waitcnt vmcnt(0)
	v_pk_fma_f32 v[130:131], v[110:111], v[138:139], v[130:131]
	v_pk_fma_f32 v[128:129], v[108:109], v[136:137], v[128:129]
	v_pk_mul_f32 v[124:125], v[92:93], v[124:125]
	v_add_u32_e32 v159, -1, v157
	v_fma_f32 v161, -v159, v157, v156
	v_add_u32_e32 v160, 1, v157
	v_cmp_ge_f32_e64 s[0:1], 0, v161
	v_and_b32_e32 v163, 0xffff0000, v122
	v_pk_fma_f32 v[124:125], v[96:97], v[132:133], v[124:125]
	v_cndmask_b32_e64 v159, v157, v159, s[0:1]
	v_fma_f32 v157, -v160, v157, v156
	v_cmp_lt_f32_e64 s[0:1], 0, v157
	s_movk_i32 s27, 0xe000
	s_nop 0
	v_cndmask_b32_e64 v157, v159, v160, s[0:1]
	v_mul_f32_e32 v159, 0x37800000, v157
	v_cndmask_b32_e32 v157, v157, v159, vcc
	v_cmp_class_f32_e32 vcc, v156, v206
	s_nop 1
	v_cndmask_b32_e32 v156, v157, v156, vcc
	v_div_scale_f32 v157, s[0:1], v156, v156, 1.0
	v_rcp_f32_e32 v159, v157
	s_mov_b64 s[0:1], 0x48000
	v_fma_f32 v160, -v157, v159, 1.0
	v_fmac_f32_e32 v159, v160, v159
	v_div_scale_f32 v160, vcc, 1.0, v156, 1.0
	v_mul_f32_e32 v161, v160, v159
	v_fma_f32 v162, -v157, v161, v160
	v_fmac_f32_e32 v161, v162, v159
	v_fma_f32 v157, -v157, v161, v160
	v_div_fmas_f32 v157, v157, v159, v161
	v_div_fixup_f32 v156, v157, v156, 1.0
	v_lshlrev_b32_e32 v160, 16, v120
	v_and_b32_e32 v161, 0xffff0000, v120
	v_lshlrev_b32_e32 v120, 16, v121
	v_and_b32_e32 v121, 0xffff0000, v121
	v_pk_mul_f32 v[118:119], v[118:119], v[156:157] op_sel_hi:[1,0]
	v_pk_fma_f32 v[120:121], v[102:103], v[120:121], v[130:131]
	v_lshlrev_b32_e32 v162, 16, v122
	v_pk_mul_f32 v[118:119], v[118:119], v[120:121]
	v_pk_mul_f32 v[120:121], v[94:95], v[126:127]
	v_lshlrev_b32_e32 v122, 16, v123
	v_and_b32_e32 v123, 0xffff0000, v123
	v_pk_mul_f32 v[116:117], v[116:117], v[156:157] op_sel_hi:[1,0]
	v_pk_fma_f32 v[128:129], v[100:101], v[160:161], v[128:129]
	v_pk_fma_f32 v[120:121], v[98:99], v[134:135], v[120:121]
	v_pk_mul_f32 v[116:117], v[116:117], v[128:129]
	v_pk_mul_f32 v[112:113], v[112:113], v[156:157] op_sel_hi:[1,0]
	v_pk_mul_f32 v[114:115], v[114:115], v[156:157] op_sel_hi:[1,0]
	v_pk_fma_f32 v[120:121], v[90:91], v[122:123], v[120:121]
	v_pk_fma_f32 v[122:123], v[88:89], v[162:163], v[124:125]
	v_pk_mul_f32 v[120:121], v[114:115], v[120:121]
	v_pk_mul_f32 v[114:115], v[112:113], v[122:123]
	v_cvt_pk_bf16_f32 v112, v116, v117
	v_lshl_add_u64 v[116:117], v[154:155], 1, s[14:15]
	v_cvt_pk_bf16_f32 v113, v118, v119
	v_cvt_pk_bf16_f32 v114, v114, v115
	v_cvt_pk_bf16_f32 v115, v120, v121
	global_store_dwordx4 v[116:117], v[112:115], off
	v_lshlrev_b64 v[116:117], 11, v[196:197]
	global_load_dword v130, v[188:189], off offset:576
	v_lshl_add_u64 v[112:113], v[116:117], 0, s[0:1]
	v_lshl_add_u64 v[114:115], v[112:113], 0, v[192:193]
	v_lshlrev_b64 v[114:115], 1, v[114:115]
	v_lshl_add_u64 v[126:127], s[12:13], 0, v[114:115]
	global_load_dwordx4 v[118:121], v[126:127], off
	global_load_dwordx4 v[122:125], v[126:127], off offset:-4096
	v_add_co_u32_e32 v126, vcc, s25, v126
	s_nop 1
	v_addc_co_u32_e32 v127, vcc, -1, v127, vcc
	global_load_dwordx4 v[126:129], v[126:127], off
	s_waitcnt vmcnt(3)
	v_fmamk_f32 v156, v130, 0x3a000000, v205
	v_mul_f32_e32 v157, 0x4f800000, v156
	v_cmp_gt_f32_e32 vcc, s83, v156
	s_waitcnt vmcnt(1)
	v_lshlrev_b32_e32 v134, 16, v122
	v_and_b32_e32 v135, 0xffff0000, v122
	v_cndmask_b32_e32 v156, v156, v157, vcc
	v_sqrt_f32_e32 v157, v156
	v_lshlrev_b32_e32 v122, 16, v123
	v_and_b32_e32 v123, 0xffff0000, v123
	v_lshlrev_b32_e32 v130, 16, v118
	v_and_b32_e32 v131, 0xffff0000, v118
	v_lshlrev_b32_e32 v118, 16, v119
	v_and_b32_e32 v119, 0xffff0000, v119
	v_lshlrev_b32_e32 v136, 16, v124
	v_and_b32_e32 v137, 0xffff0000, v124
	v_lshlrev_b32_e32 v124, 16, v125
	v_and_b32_e32 v125, 0xffff0000, v125
	v_lshlrev_b32_e32 v132, 16, v120
	v_and_b32_e32 v133, 0xffff0000, v120
	v_lshlrev_b32_e32 v120, 16, v121
	v_and_b32_e32 v121, 0xffff0000, v121
	s_waitcnt vmcnt(0)
	v_lshlrev_b32_e32 v138, 16, v126
	v_and_b32_e32 v139, 0xffff0000, v126
	v_lshlrev_b32_e32 v126, 16, v127
	v_and_b32_e32 v127, 0xffff0000, v127
	v_pk_mul_f32 v[126:127], v[110:111], v[126:127]
	v_pk_mul_f32 v[138:139], v[108:109], v[138:139]
	v_pk_fma_f32 v[122:123], v[106:107], v[122:123], v[126:127]
	v_add_u32_e32 v126, -1, v157
	v_add_u32_e32 v127, 1, v157
	v_fma_f32 v159, -v126, v157, v156
	v_fma_f32 v160, -v127, v157, v156
	v_cmp_ge_f32_e64 s[0:1], 0, v159
	v_lshlrev_b32_e32 v154, 16, v128
	v_and_b32_e32 v155, 0xffff0000, v128
	v_cndmask_b32_e64 v126, v157, v126, s[0:1]
	v_cmp_lt_f32_e64 s[0:1], 0, v160
	v_lshlrev_b32_e32 v128, 16, v129
	v_and_b32_e32 v129, 0xffff0000, v129
	v_cndmask_b32_e64 v126, v126, v127, s[0:1]
	v_mul_f32_e32 v127, 0x37800000, v126
	v_cndmask_b32_e32 v126, v126, v127, vcc
	v_cmp_class_f32_e32 vcc, v156, v206
	v_pk_fma_f32 v[118:119], v[102:103], v[118:119], v[122:123]
	v_pk_mul_f32 v[122:123], v[98:99], v[128:129]
	v_cndmask_b32_e32 v156, v126, v156, vcc
	v_div_scale_f32 v157, s[0:1], v156, v156, 1.0
	v_rcp_f32_e32 v159, v157
	v_pk_fma_f32 v[126:127], v[104:105], v[134:135], v[138:139]
	v_div_scale_f32 v134, vcc, 1.0, v156, 1.0
	v_fma_f32 v135, -v157, v159, 1.0
	v_fmac_f32_e32 v159, v135, v159
	v_mul_f32_e32 v135, v134, v159
	v_fma_f32 v138, -v157, v135, v134
	v_fmac_f32_e32 v135, v138, v159
	v_fma_f32 v134, -v157, v135, v134
	v_div_fmas_f32 v134, v134, v159, v135
	v_div_fixup_f32 v134, v134, v156, 1.0
; __device__ __forceinline__ u32x4 pack8(f32x4 a, f32x4 b) { u32x4 w; w.x = cvt_pk_bf16(a[0], a[1]); w.y = cvt_pk_bf16(a[2], a[3]); w.z = cvt_pk_bf16(b[0], b[1]); w.w = cvt_pk_bf16(b[2], b[3]); return w; }
; __device__ __forceinline__ float rs_of(const float* ss, int row) { return 1.0f / sqrtf(ss[row] * (1.0f / 2048.0f) + 1e-5f); }
;     __device__ __forceinline__ void operator()(const f32x4 (&acc)[2][2][4][2], const Unit& u, int wr, int wc, int fr, int fq) const {
;     ...
;                     const int row = row0 + ai * HALF + m * 16, s = row & 8191; const float rr = rs_of(ss, row);
;                     const size_t off = (size_t)row * 2048 + ch0;
;                     f32x4 c0a, c0b, p1a, p1b, p2a, p2b;
;                     unpk(*(const u32x4*)(V + off), c0a, c0b);
;                     if (s >= 2) { unpk(*(const u32x4*)(V + off - 2048), p1a, p1b); unpk(*(const u32x4*)(V + off - 4096), p2a, p2b); }
;                     else if (s == 1) { unpk(*(const u32x4*)(V + off - 2048), p1a, p1b); p2a = *(const f32x4*)(Vm + 15 * 2048 + ch0); p2b = *(const f32x4*)(Vm + 15 * 2048 + ch0 + 4); }
;                     else { p1a = *(const f32x4*)(Vm + 15 * 2048 + ch0); p1b = *(const f32x4*)(Vm + 15 * 2048 + ch0 + 4); p2a = *(const f32x4*)(Vm + 14 * 2048 + ch0); p2b = *(const f32x4*)(Vm + 14 * 2048 + ch0 + 4); }
;                     const f32x4 za = (acc[ai][bj][m][0] * rr) * (w0a * p2a + w1a * p1a + w2a * c0a);
;                     const f32x4 zb = (acc[ai][bj][m][1] * rr) * (w0b * p2b + w1b * p1b + w2b * c0b);
;                     *(u32x4*)(Z + off) = pack8(za, zb);
;                     if (m & 1) asm volatile("" ::: "memory");
	v_pk_mul_f32 v[86:87], v[86:87], v[134:135] op_sel_hi:[1,0]
	v_pk_mul_f32 v[84:85], v[84:85], v[134:135] op_sel_hi:[1,0]
	v_pk_mul_f32 v[86:87], v[86:87], v[118:119]
	v_pk_mul_f32 v[118:119], v[96:97], v[154:155]
	v_pk_fma_f32 v[126:127], v[100:101], v[130:131], v[126:127]
	v_pk_fma_f32 v[122:123], v[94:95], v[124:125], v[122:123]
	v_pk_fma_f32 v[118:119], v[92:93], v[136:137], v[118:119]
	v_pk_mul_f32 v[84:85], v[84:85], v[126:127]
	v_pk_mul_f32 v[80:81], v[80:81], v[134:135] op_sel_hi:[1,0]
	v_pk_mul_f32 v[82:83], v[82:83], v[134:135] op_sel_hi:[1,0]
	v_pk_fma_f32 v[118:119], v[88:89], v[132:133], v[118:119]
	v_pk_fma_f32 v[120:121], v[90:91], v[120:121], v[122:123]
	s_mov_b64 s[0:1], 0x50000
	v_pk_mul_f32 v[120:121], v[82:83], v[120:121]
	v_pk_mul_f32 v[82:83], v[80:81], v[118:119]
	v_cvt_pk_bf16_f32 v80, v84, v85
	v_cvt_pk_bf16_f32 v81, v86, v87
	v_lshl_add_u64 v[84:85], s[14:15], 0, v[114:115]
	v_lshl_add_u64 v[114:115], v[116:117], 0, s[0:1]
	v_cvt_pk_bf16_f32 v82, v82, v83
	v_cvt_pk_bf16_f32 v83, v120, v121
	global_store_dwordx4 v[84:85], v[80:83], off
	global_load_dword v124, v[188:189], off offset:640
	s_mov_b64 s[0:1], 0x58000
	v_lshl_add_u64 v[80:81], v[114:115], 0, v[192:193]
	v_lshlrev_b64 v[122:123], 1, v[80:81]
	v_lshl_add_u64 v[118:119], s[12:13], 0, v[122:123]
	global_load_dwordx4 v[80:83], v[118:119], off
	global_load_dwordx4 v[84:87], v[118:119], off offset:-4096
	v_add_co_u32_e32 v118, vcc, s25, v118
	v_lshl_add_u64 v[116:117], v[116:117], 0, s[0:1]
	s_nop 0
	v_addc_co_u32_e32 v119, vcc, -1, v119, vcc
	global_load_dwordx4 v[118:121], v[118:119], off
	v_lshl_add_u64 v[122:123], s[14:15], 0, v[122:123]
	s_waitcnt vmcnt(3)
	v_fmamk_f32 v136, v124, 0x3a000000, v205
	v_mul_f32_e32 v137, 0x4f800000, v136
	v_cmp_gt_f32_e32 vcc, s83, v136
	s_waitcnt vmcnt(2)
	v_lshlrev_b32_e32 v124, 16, v80
	s_waitcnt vmcnt(1)
	v_lshlrev_b32_e32 v128, 16, v84
	v_and_b32_e32 v129, 0xffff0000, v84
	v_lshlrev_b32_e32 v84, 16, v85
	v_and_b32_e32 v85, 0xffff0000, v85
	v_cndmask_b32_e32 v136, v136, v137, vcc
	v_lshlrev_b32_e32 v130, 16, v86
	s_waitcnt vmcnt(0)
	v_lshlrev_b32_e32 v132, 16, v118
	v_and_b32_e32 v133, 0xffff0000, v118
	v_lshlrev_b32_e32 v118, 16, v119
	v_and_b32_e32 v119, 0xffff0000, v119
	v_pk_mul_f32 v[132:133], v[108:109], v[132:133]
	v_pk_mul_f32 v[118:119], v[110:111], v[118:119]
	v_lshlrev_b32_e32 v134, 16, v120
	v_pk_fma_f32 v[84:85], v[106:107], v[84:85], v[118:119]
	v_pk_fma_f32 v[118:119], v[104:105], v[128:129], v[132:133]
	v_sqrt_f32_e32 v128, v136
	v_and_b32_e32 v135, 0xffff0000, v120
	v_lshlrev_b32_e32 v120, 16, v121
	v_and_b32_e32 v121, 0xffff0000, v121
	v_and_b32_e32 v131, 0xffff0000, v86
	v_lshlrev_b32_e32 v86, 16, v87
	v_and_b32_e32 v87, 0xffff0000, v87
	v_pk_mul_f32 v[134:135], v[96:97], v[134:135]
	v_pk_mul_f32 v[120:121], v[98:99], v[120:121]
	v_and_b32_e32 v125, 0xffff0000, v80
	v_lshlrev_b32_e32 v80, 16, v81
	v_and_b32_e32 v81, 0xffff0000, v81
	v_lshlrev_b32_e32 v126, 16, v82
	v_and_b32_e32 v127, 0xffff0000, v82
	v_pk_fma_f32 v[86:87], v[94:95], v[86:87], v[120:121]
	v_pk_fma_f32 v[120:121], v[92:93], v[130:131], v[134:135]
	v_pk_fma_f32 v[80:81], v[102:103], v[80:81], v[84:85]
	v_pk_fma_f32 v[84:85], v[88:89], v[126:127], v[120:121]
	v_add_u32_e32 v120, -1, v128
	v_pk_fma_f32 v[118:119], v[100:101], v[124:125], v[118:119]
	v_add_u32_e32 v121, 1, v128
	v_fma_f32 v124, -v120, v128, v136
	v_fma_f32 v125, -v121, v128, v136
	v_cmp_ge_f32_e64 s[0:1], 0, v124
	v_lshlrev_b32_e32 v82, 16, v83
	v_and_b32_e32 v83, 0xffff0000, v83
	v_cndmask_b32_e64 v120, v128, v120, s[0:1]
	v_cmp_lt_f32_e64 s[0:1], 0, v125
	v_pk_fma_f32 v[82:83], v[90:91], v[82:83], v[86:87]
	s_nop 0
	v_cndmask_b32_e64 v120, v120, v121, s[0:1]
	v_mul_f32_e32 v121, 0x37800000, v120
	v_cndmask_b32_e32 v120, v120, v121, vcc
	v_cmp_class_f32_e32 vcc, v136, v206
	s_nop 1
	v_cndmask_b32_e32 v120, v120, v136, vcc
	v_div_scale_f32 v121, s[0:1], v120, v120, 1.0
	v_rcp_f32_e32 v124, v121
	v_div_scale_f32 v86, vcc, 1.0, v120, 1.0
	v_readlane_b32 s0, v254, 38
	v_fma_f32 v87, -v121, v124, 1.0
	v_fmac_f32_e32 v124, v87, v124
	v_mul_f32_e32 v87, v86, v124
	v_fma_f32 v125, -v121, v87, v86
	v_fmac_f32_e32 v87, v125, v124
	v_fma_f32 v86, -v121, v87, v86
	v_div_fmas_f32 v86, v86, v124, v87
	v_div_fixup_f32 v86, v86, v120, 1.0
	v_pk_mul_f32 v[76:77], v[76:77], v[86:87] op_sel_hi:[1,0]
	v_pk_mul_f32 v[78:79], v[78:79], v[86:87] op_sel_hi:[1,0]
	v_pk_mul_f32 v[72:73], v[72:73], v[86:87] op_sel_hi:[1,0]
	v_pk_mul_f32 v[74:75], v[74:75], v[86:87] op_sel_hi:[1,0]
	v_pk_mul_f32 v[78:79], v[78:79], v[80:81]
	v_pk_mul_f32 v[76:77], v[76:77], v[118:119]
	v_pk_mul_f32 v[80:81], v[74:75], v[82:83]
	v_pk_mul_f32 v[74:75], v[72:73], v[84:85]
	v_cvt_pk_bf16_f32 v72, v76, v77
	v_cvt_pk_bf16_f32 v73, v78, v79
	v_or_b32_e32 v118, 32, v192
	v_cvt_pk_bf16_f32 v74, v74, v75
	v_cvt_pk_bf16_f32 v75, v80, v81
	global_store_dwordx4 v[122:123], v[72:75], off
	global_load_dword v86, v[188:189], off offset:704
	v_ashrrev_i32_e32 v119, 31, v118
	v_lshl_add_u64 v[72:73], v[116:117], 0, v[192:193]
	v_lshlrev_b64 v[84:85], 1, v[72:73]
	v_lshl_add_u64 v[80:81], s[12:13], 0, v[84:85]
	global_load_dwordx4 v[72:75], v[80:81], off
	global_load_dwordx4 v[76:79], v[80:81], off offset:-4096
	v_add_co_u32_e32 v80, vcc, s25, v80
	v_lshlrev_b64 v[120:121], 2, v[118:119]
	s_nop 0
	v_addc_co_u32_e32 v81, vcc, -1, v81, vcc
	global_load_dwordx4 v[80:83], v[80:81], off
	v_readlane_b32 s1, v254, 39
	v_lshl_add_u64 v[84:85], s[14:15], 0, v[84:85]
	v_lshl_add_u64 v[122:123], v[194:195], 0, v[118:119]
	v_lshl_add_u64 v[126:127], s[0:1], 0, v[120:121]
	v_readlane_b32 s0, v254, 40
	v_readlane_b32 s1, v254, 41
	v_lshl_add_u64 v[124:125], v[122:123], 1, s[12:13]
	s_waitcnt vmcnt(3)
; __device__ __forceinline__ float rs_of(const float* ss, int row) { return 1.0f / sqrtf(ss[row] * (1.0f / 2048.0f) + 1e-5f); }
;     __device__ __forceinline__ void operator()(const f32x4 (&acc)[2][2][4][2], const Unit& u, int wr, int wc, int fr, int fq) const {
;     ...
;             const int ch0 = u.pn * BM + wc * 64 + bj * 32 + 8 * fq;
;             const f32x4 w0a = *(const f32x4*)(cw + ch0), w0b = *(const f32x4*)(cw + ch0 + 4);
;             const f32x4 w1a = *(const f32x4*)(cw + 2048 + ch0), w1b = *(const f32x4*)(cw + 2048 + ch0 + 4);
;             const f32x4 w2a = *(const f32x4*)(cw + 4096 + ch0), w2b = *(const f32x4*)(cw + 4096 + ch0 + 4);
; #pragma unroll
;             for (int ai = 0; ai < 2; ++ai)
; #pragma unroll
;                 for (int m = 0; m < 4; ++m) {
;                     const int row = row0 + ai * HALF + m * 16, s = row & 8191; const float rr = rs_of(ss, row);
;                     const size_t off = (size_t)row * 2048 + ch0;
;                     f32x4 c0a, c0b, p1a, p1b, p2a, p2b;
;                     unpk(*(const u32x4*)(V + off), c0a, c0b);
;                     if (s >= 2) { unpk(*(const u32x4*)(V + off - 2048), p1a, p1b); unpk(*(const u32x4*)(V + off - 4096), p2a, p2b); }
;                     else if (s == 1) { unpk(*(const u32x4*)(V + off - 2048), p1a, p1b); p2a = *(const f32x4*)(Vm + 15 * 2048 + ch0); p2b = *(const f32x4*)(Vm + 15 * 2048 + ch0 + 4); }
;                     else { p1a = *(const f32x4*)(Vm + 15 * 2048 + ch0); p1b = *(const f32x4*)(Vm + 15 * 2048 + ch0 + 4); p2a = *(const f32x4*)(Vm + 14 * 2048 + ch0); p2b = *(const f32x4*)(Vm + 14 * 2048 + ch0 + 4); }
	v_fmamk_f32 v154, v86, 0x3a000000, v205
	v_mul_f32_e32 v155, 0x4f800000, v154
	v_cmp_gt_f32_e32 vcc, s83, v154
	v_lshl_add_u64 v[128:129], s[0:1], 0, v[120:121]
	s_waitcnt vmcnt(2)
	v_lshlrev_b32_e32 v86, 16, v72
	s_waitcnt vmcnt(1)
	v_lshlrev_b32_e32 v134, 16, v78
	v_and_b32_e32 v135, 0xffff0000, v78
	v_lshlrev_b32_e32 v78, 16, v79
	v_and_b32_e32 v79, 0xffff0000, v79
	v_lshlrev_b32_e32 v132, 16, v76
	v_and_b32_e32 v133, 0xffff0000, v76
	s_waitcnt vmcnt(0)
	v_lshlrev_b32_e32 v138, 16, v82
	v_and_b32_e32 v139, 0xffff0000, v82
	v_lshlrev_b32_e32 v82, 16, v83
	v_and_b32_e32 v83, 0xffff0000, v83
	v_pk_mul_f32 v[96:97], v[96:97], v[138:139]
	v_pk_mul_f32 v[82:83], v[98:99], v[82:83]
	v_cndmask_b32_e32 v98, v154, v155, vcc
	v_pk_fma_f32 v[78:79], v[94:95], v[78:79], v[82:83]
	v_pk_fma_f32 v[82:83], v[92:93], v[134:135], v[96:97]
	v_sqrt_f32_e32 v92, v98
	v_lshlrev_b32_e32 v136, 16, v80
	v_and_b32_e32 v137, 0xffff0000, v80
	v_lshlrev_b32_e32 v80, 16, v81
	v_and_b32_e32 v81, 0xffff0000, v81
	v_lshlrev_b32_e32 v76, 16, v77
	v_and_b32_e32 v77, 0xffff0000, v77
	v_pk_mul_f32 v[80:81], v[110:111], v[80:81]
	v_and_b32_e32 v87, 0xffff0000, v72
	v_lshlrev_b32_e32 v72, 16, v73
	v_and_b32_e32 v73, 0xffff0000, v73
	v_lshlrev_b32_e32 v130, 16, v74
	v_and_b32_e32 v131, 0xffff0000, v74
	v_pk_mul_f32 v[108:109], v[108:109], v[136:137]
	v_pk_fma_f32 v[76:77], v[106:107], v[76:77], v[80:81]
	v_pk_fma_f32 v[80:81], v[104:105], v[132:133], v[108:109]
	v_pk_fma_f32 v[72:73], v[102:103], v[72:73], v[76:77]
	v_pk_fma_f32 v[76:77], v[88:89], v[130:131], v[82:83]
	v_add_u32_e32 v82, -1, v92
	v_pk_fma_f32 v[80:81], v[100:101], v[86:87], v[80:81]
	v_add_u32_e32 v83, 1, v92
	v_fma_f32 v86, -v82, v92, v98
	v_fma_f32 v87, -v83, v92, v98
	v_cmp_ge_f32_e64 s[0:1], 0, v86
	v_lshlrev_b32_e32 v74, 16, v75
	v_and_b32_e32 v75, 0xffff0000, v75
	v_cndmask_b32_e64 v82, v92, v82, s[0:1]
	v_cmp_lt_f32_e64 s[0:1], 0, v87
	v_pk_fma_f32 v[74:75], v[90:91], v[74:75], v[78:79]
	s_nop 0
	v_cndmask_b32_e64 v82, v82, v83, s[0:1]
	v_mul_f32_e32 v83, 0x37800000, v82
	v_cndmask_b32_e32 v82, v82, v83, vcc
	v_cmp_class_f32_e32 vcc, v98, v206
	s_nop 1
	v_cndmask_b32_e32 v82, v82, v98, vcc
	v_div_scale_f32 v83, s[0:1], v82, v82, 1.0
	v_rcp_f32_e32 v86, v83
	v_div_scale_f32 v78, vcc, 1.0, v82, 1.0
	v_fma_f32 v79, -v83, v86, 1.0
	v_fmac_f32_e32 v86, v79, v86
	v_mul_f32_e32 v79, v78, v86
	v_fma_f32 v87, -v83, v79, v78
	v_fmac_f32_e32 v79, v87, v86
	v_fma_f32 v78, -v83, v79, v78
	v_div_fmas_f32 v78, v78, v86, v79
	v_div_fixup_f32 v78, v78, v82, 1.0
	v_pk_mul_f32 v[70:71], v[70:71], v[78:79] op_sel_hi:[1,0]
	v_pk_mul_f32 v[64:65], v[64:65], v[78:79] op_sel_hi:[1,0]
	v_pk_mul_f32 v[66:67], v[66:67], v[78:79] op_sel_hi:[1,0]
	v_pk_mul_f32 v[68:69], v[68:69], v[78:79] op_sel_hi:[1,0]
	v_pk_mul_f32 v[70:71], v[70:71], v[72:73]
	v_pk_mul_f32 v[72:73], v[66:67], v[74:75]
	v_pk_mul_f32 v[66:67], v[64:65], v[76:77]
	v_pk_mul_f32 v[68:69], v[68:69], v[80:81]
	s_nop 0
	v_cvt_pk_bf16_f32 v64, v68, v69
	v_cvt_pk_bf16_f32 v65, v70, v71
	v_cvt_pk_bf16_f32 v66, v66, v67
	v_cvt_pk_bf16_f32 v67, v72, v73
	global_store_dwordx4 v[84:85], v[64:67], off
	global_load_dwordx4 v[80:83], v[190:191], off offset:144
	global_load_dwordx4 v[84:87], v[190:191], off offset:128
	global_load_dwordx4 v[68:71], v[126:127], off offset:16
	global_load_dwordx4 v[76:79], v[126:127], off
	global_load_dwordx4 v[64:67], v[128:129], off offset:16
	global_load_dwordx4 v[72:75], v[128:129], off
	global_load_dword v108, v[188:189], off
	global_load_dwordx4 v[88:91], v[124:125], off
	s_and_saveexec_b64 s[0:1], s[4:5]
	s_xor_b64 s[0:1], exec, s[0:1]
	s_cbranch_execz .LBB0_528
	v_cmp_ne_u32_e32 vcc, 1, v216
	s_and_saveexec_b64 s[4:5], vcc
	s_xor_b64 s[4:5], exec, s[4:5]
	s_cbranch_execz .LBB0_525
	v_lshl_add_u64 v[96:97], s[20:21], 0, v[120:121]
	v_lshl_add_u64 v[104:105], s[22:23], 0, v[120:121]
	global_load_dwordx4 v[92:95], v[96:97], off offset:16
	s_nop 0
	global_load_dwordx4 v[96:99], v[96:97], off
	s_nop 0
	global_load_dwordx4 v[100:103], v[104:105], off offset:16
	s_nop 0
	global_load_dwordx4 v[104:107], v[104:105], off

; __device__ __forceinline__ u32x4 pack8(f32x4 a, f32x4 b) { u32x4 w; w.x = cvt_pk_bf16(a[0], a[1]); w.y = cvt_pk_bf16(a[2], a[3]); w.z = cvt_pk_bf16(b[0], b[1]); w.w = cvt_pk_bf16(b[2], b[3]); return w; }
; __device__ __forceinline__ float rs_of(const float* ss, int row) { return 1.0f / sqrtf(ss[row] * (1.0f / 2048.0f) + 1e-5f); }
;     __device__ __forceinline__ void operator()(const f32x4 (&acc)[2][2][4][2], const Unit& u, int wr, int wc, int fr, int fq) const {
;     ...
;                     const int row = row0 + ai * HALF + m * 16, s = row & 8191; const float rr = rs_of(ss, row);
;                     const size_t off = (size_t)row * 2048 + ch0;
;                     f32x4 c0a, c0b, p1a, p1b, p2a, p2b;
;                     unpk(*(const u32x4*)(V + off), c0a, c0b);
;                     if (s >= 2) { unpk(*(const u32x4*)(V + off - 2048), p1a, p1b); unpk(*(const u32x4*)(V + off - 4096), p2a, p2b); }
;                     else if (s == 1) { unpk(*(const u32x4*)(V + off - 2048), p1a, p1b); p2a = *(const f32x4*)(Vm + 15 * 2048 + ch0); p2b = *(const f32x4*)(Vm + 15 * 2048 + ch0 + 4); }
;                     else { p1a = *(const f32x4*)(Vm + 15 * 2048 + ch0); p1b = *(const f32x4*)(Vm + 15 * 2048 + ch0 + 4); p2a = *(const f32x4*)(Vm + 14 * 2048 + ch0); p2b = *(const f32x4*)(Vm + 14 * 2048 + ch0 + 4); }
;                     const f32x4 za = (acc[ai][bj][m][0] * rr) * (w0a * p2a + w1a * p1a + w2a * c0a);
;                     const f32x4 zb = (acc[ai][bj][m][1] * rr) * (w0b * p2b + w1b * p1b + w2b * c0b);
;                     *(u32x4*)(Z + off) = pack8(za, zb);
;                     if (m & 1) asm volatile("" ::: "memory");
.LBB0_530:
	s_or_b64 exec, exec, s[0:1]
	s_waitcnt vmcnt(1)
	v_fmamk_f32 v108, v108, 0x3a000000, v205
	v_mul_f32_e32 v109, 0x4f800000, v108
	v_cmp_gt_f32_e32 vcc, s83, v108
	v_pk_mul_f32 v[98:99], v[78:79], v[98:99]
	v_pk_mul_f32 v[96:97], v[76:77], v[96:97]
	v_cndmask_b32_e32 v108, v108, v109, vcc
	v_sqrt_f32_e32 v109, v108
	s_waitcnt vmcnt(0)
	v_pk_fma_f32 v[98:99], v[86:87], v[106:107], v[98:99]
	v_pk_fma_f32 v[96:97], v[84:85], v[104:105], v[96:97]
	v_pk_mul_f32 v[92:93], v[68:69], v[92:93]
	v_add_u32_e32 v110, -1, v109
	v_fma_f32 v124, -v110, v109, v108
	v_add_u32_e32 v111, 1, v109
	v_cmp_ge_f32_e64 s[0:1], 0, v124
	v_pk_fma_f32 v[92:93], v[80:81], v[100:101], v[92:93]
	s_movk_i32 s4, 0xe000
	v_cndmask_b32_e64 v110, v109, v110, s[0:1]
	v_fma_f32 v109, -v111, v109, v108
	v_cmp_lt_f32_e64 s[0:1], 0, v109
	s_nop 1
	v_cndmask_b32_e64 v109, v110, v111, s[0:1]
	v_mul_f32_e32 v110, 0x37800000, v109
	v_cndmask_b32_e32 v109, v109, v110, vcc
	v_cmp_class_f32_e32 vcc, v108, v206
	s_nop 1
	v_cndmask_b32_e32 v108, v109, v108, vcc
	v_div_scale_f32 v109, s[0:1], v108, v108, 1.0
	v_rcp_f32_e32 v110, v109
	s_nop 0
	v_fma_f32 v111, -v109, v110, 1.0
	v_fmac_f32_e32 v110, v111, v110
	v_div_scale_f32 v111, vcc, 1.0, v108, 1.0
	v_mul_f32_e32 v124, v111, v110
	v_fma_f32 v125, -v109, v124, v111
	v_fmac_f32_e32 v124, v125, v110
	v_fma_f32 v109, -v109, v124, v111
	v_div_fmas_f32 v109, v109, v110, v124
	v_div_fixup_f32 v108, v109, v108, 1.0
	v_lshlrev_b32_e32 v110, 16, v88
	v_and_b32_e32 v111, 0xffff0000, v88
	v_lshlrev_b32_e32 v88, 16, v89
	v_and_b32_e32 v89, 0xffff0000, v89
	v_pk_mul_f32 v[62:63], v[62:63], v[108:109] op_sel_hi:[1,0]
	v_pk_fma_f32 v[88:89], v[74:75], v[88:89], v[98:99]
	v_lshlrev_b32_e32 v124, 16, v90
	v_pk_mul_f32 v[62:63], v[62:63], v[88:89]
	v_pk_mul_f32 v[88:89], v[70:71], v[94:95]
	v_and_b32_e32 v125, 0xffff0000, v90
	v_lshlrev_b32_e32 v90, 16, v91
	v_and_b32_e32 v91, 0xffff0000, v91
	v_pk_mul_f32 v[60:61], v[60:61], v[108:109] op_sel_hi:[1,0]
	v_pk_fma_f32 v[96:97], v[72:73], v[110:111], v[96:97]
	v_pk_fma_f32 v[88:89], v[82:83], v[102:103], v[88:89]
	v_pk_mul_f32 v[60:61], v[60:61], v[96:97]
	v_pk_mul_f32 v[56:57], v[56:57], v[108:109] op_sel_hi:[1,0]
	v_pk_mul_f32 v[58:59], v[58:59], v[108:109] op_sel_hi:[1,0]
	v_pk_fma_f32 v[92:93], v[64:65], v[124:125], v[92:93]
	v_pk_fma_f32 v[88:89], v[66:67], v[90:91], v[88:89]
	s_nop 0
	v_pk_mul_f32 v[88:89], v[58:59], v[88:89]
	v_pk_mul_f32 v[58:59], v[56:57], v[92:93]
	v_cvt_pk_bf16_f32 v56, v60, v61
	v_cvt_pk_bf16_f32 v57, v62, v63
	v_lshl_add_u64 v[60:61], v[122:123], 1, s[14:15]
	v_cvt_pk_bf16_f32 v58, v58, v59
	v_cvt_pk_bf16_f32 v59, v88, v89
	global_store_dwordx4 v[60:61], v[56:59], off
	global_load_dword v94, v[144:145], off
	s_nop 1
	v_lshl_add_u64 v[56:57], v[146:147], 0, v[118:119]
	v_lshlrev_b64 v[92:93], 1, v[56:57]
	v_lshl_add_u64 v[88:89], s[12:13], 0, v[92:93]
	global_load_dwordx4 v[56:59], v[88:89], off
	global_load_dwordx4 v[60:63], v[88:89], off offset:-4096
	v_add_co_u32_e32 v88, vcc, s4, v88
	s_nop 0
	s_nop 0
	v_addc_co_u32_e32 v89, vcc, -1, v89, vcc
	global_load_dwordx4 v[88:91], v[88:89], off
	s_waitcnt vmcnt(3)
	v_fmamk_f32 v106, v94, 0x3a000000, v205
	v_mul_f32_e32 v107, 0x4f800000, v106
	v_cmp_gt_f32_e32 vcc, s83, v106
	s_waitcnt vmcnt(2)
	v_lshlrev_b32_e32 v94, 16, v56
	v_cndmask_b32_e32 v106, v106, v107, vcc
	v_sqrt_f32_e32 v107, v106
	s_waitcnt vmcnt(1)
	v_lshlrev_b32_e32 v98, 16, v60
	v_and_b32_e32 v99, 0xffff0000, v60
	v_lshlrev_b32_e32 v60, 16, v61
	v_and_b32_e32 v61, 0xffff0000, v61
	s_waitcnt vmcnt(0)
	v_lshlrev_b32_e32 v102, 16, v88
	v_and_b32_e32 v103, 0xffff0000, v88
	v_lshlrev_b32_e32 v88, 16, v89
	v_and_b32_e32 v89, 0xffff0000, v89
	v_pk_mul_f32 v[102:103], v[84:85], v[102:103]
	v_pk_mul_f32 v[88:89], v[86:87], v[88:89]
	v_and_b32_e32 v95, 0xffff0000, v56
	v_pk_fma_f32 v[60:61], v[78:79], v[60:61], v[88:89]
	v_pk_fma_f32 v[88:89], v[76:77], v[98:99], v[102:103]
	v_lshlrev_b32_e32 v56, 16, v57
	v_pk_fma_f32 v[88:89], v[72:73], v[94:95], v[88:89]
	v_add_u32_e32 v94, -1, v107
	v_add_u32_e32 v95, 1, v107
	v_fma_f32 v98, -v94, v107, v106
	v_fma_f32 v99, -v95, v107, v106
	v_cmp_ge_f32_e64 s[0:1], 0, v98
	v_and_b32_e32 v57, 0xffff0000, v57
	v_pk_fma_f32 v[56:57], v[74:75], v[56:57], v[60:61]
	v_cndmask_b32_e64 v94, v107, v94, s[0:1]
	v_cmp_lt_f32_e64 s[0:1], 0, v99
	v_lshlrev_b32_e32 v104, 16, v90
	v_and_b32_e32 v105, 0xffff0000, v90
	v_cndmask_b32_e64 v94, v94, v95, s[0:1]
	v_mul_f32_e32 v95, 0x37800000, v94
	v_cndmask_b32_e32 v94, v94, v95, vcc
	v_cmp_class_f32_e32 vcc, v106, v206
	v_lshlrev_b32_e32 v90, 16, v91
	v_and_b32_e32 v91, 0xffff0000, v91
	v_cndmask_b32_e32 v94, v94, v106, vcc
	v_div_scale_f32 v95, s[0:1], v94, v94, 1.0
	v_rcp_f32_e32 v98, v95
	v_div_scale_f32 v60, vcc, 1.0, v94, 1.0
	v_lshlrev_b32_e32 v100, 16, v62
	v_fma_f32 v61, -v95, v98, 1.0
	v_fmac_f32_e32 v98, v61, v98
	v_mul_f32_e32 v61, v60, v98
	v_fma_f32 v99, -v95, v61, v60
	v_fmac_f32_e32 v61, v99, v98
	v_fma_f32 v60, -v95, v61, v60
	v_div_fmas_f32 v60, v60, v98, v61
	v_div_fixup_f32 v60, v60, v94, 1.0
	v_pk_mul_f32 v[54:55], v[54:55], v[60:61] op_sel_hi:[1,0]
	v_and_b32_e32 v101, 0xffff0000, v62
	v_lshlrev_b32_e32 v62, 16, v63
	v_and_b32_e32 v63, 0xffff0000, v63
	v_pk_mul_f32 v[52:53], v[52:53], v[60:61] op_sel_hi:[1,0]
	v_pk_mul_f32 v[54:55], v[54:55], v[56:57]
	v_pk_mul_f32 v[48:49], v[48:49], v[60:61] op_sel_hi:[1,0]
	v_pk_mul_f32 v[50:51], v[50:51], v[60:61] op_sel_hi:[1,0]
	v_pk_mul_f32 v[56:57], v[80:81], v[104:105]
	v_pk_mul_f32 v[60:61], v[82:83], v[90:91]
	v_lshlrev_b32_e32 v96, 16, v58
	v_and_b32_e32 v97, 0xffff0000, v58
	v_lshlrev_b32_e32 v58, 16, v59
	v_and_b32_e32 v59, 0xffff0000, v59
	v_pk_fma_f32 v[60:61], v[70:71], v[62:63], v[60:61]
	v_pk_fma_f32 v[56:57], v[68:69], v[100:101], v[56:57]
	v_pk_mul_f32 v[52:53], v[52:53], v[88:89]
	v_pk_fma_f32 v[56:57], v[64:65], v[96:97], v[56:57]
	v_pk_fma_f32 v[58:59], v[66:67], v[58:59], v[60:61]
	v_lshl_add_u64 v[62:63], v[152:153], 0, v[118:119]
	v_pk_mul_f32 v[58:59], v[50:51], v[58:59]
	v_pk_mul_f32 v[50:51], v[48:49], v[56:57]
	v_cvt_pk_bf16_f32 v48, v52, v53
	v_cvt_pk_bf16_f32 v49, v54, v55
	v_lshl_add_u64 v[52:53], s[14:15], 0, v[92:93]
	v_cvt_pk_bf16_f32 v50, v50, v51
	v_cvt_pk_bf16_f32 v51, v58, v59
	global_store_dwordx4 v[52:53], v[48:51], off
	global_load_dword v90, v[148:149], off
	v_lshlrev_b64 v[62:63], 1, v[62:63]
	v_lshl_add_u64 v[48:49], v[150:151], 0, v[118:119]
	v_lshlrev_b64 v[60:61], 1, v[48:49]
	v_lshl_add_u64 v[56:57], s[12:13], 0, v[60:61]
	global_load_dwordx4 v[48:51], v[56:57], off
	global_load_dwordx4 v[52:55], v[56:57], off offset:-4096
	v_add_co_u32_e32 v56, vcc, s4, v56
	v_lshl_add_u64 v[88:89], s[12:13], 0, v[62:63]
	s_nop 0
	v_addc_co_u32_e32 v57, vcc, -1, v57, vcc
	global_load_dwordx4 v[56:59], v[56:57], off
	v_lshl_add_u64 v[60:61], s[14:15], 0, v[60:61]
	s_waitcnt vmcnt(3)
; __device__ __forceinline__ u32x4 pack8(f32x4 a, f32x4 b) { u32x4 w; w.x = cvt_pk_bf16(a[0], a[1]); w.y = cvt_pk_bf16(a[2], a[3]); w.z = cvt_pk_bf16(b[0], b[1]); w.w = cvt_pk_bf16(b[2], b[3]); return w; }
; __device__ __forceinline__ float rs_of(const float* ss, int row) { return 1.0f / sqrtf(ss[row] * (1.0f / 2048.0f) + 1e-5f); }
;     __device__ __forceinline__ void operator()(const f32x4 (&acc)[2][2][4][2], const Unit& u, int wr, int wc, int fr, int fq) const {
;     ...
;                 for (int m = 0; m < 4; ++m) {
;                     const int row = row0 + ai * HALF + m * 16, s = row & 8191; const float rr = rs_of(ss, row);
;                     const size_t off = (size_t)row * 2048 + ch0;
;                     f32x4 c0a, c0b, p1a, p1b, p2a, p2b;
;                     unpk(*(const u32x4*)(V + off), c0a, c0b);
;                     if (s >= 2) { unpk(*(const u32x4*)(V + off - 2048), p1a, p1b); unpk(*(const u32x4*)(V + off - 4096), p2a, p2b); }
;                     else if (s == 1) { unpk(*(const u32x4*)(V + off - 2048), p1a, p1b); p2a = *(const f32x4*)(Vm + 15 * 2048 + ch0); p2b = *(const f32x4*)(Vm + 15 * 2048 + ch0 + 4); }
;                     else { p1a = *(const f32x4*)(Vm + 15 * 2048 + ch0); p1b = *(const f32x4*)(Vm + 15 * 2048 + ch0 + 4); p2a = *(const f32x4*)(Vm + 14 * 2048 + ch0); p2b = *(const f32x4*)(Vm + 14 * 2048 + ch0 + 4); }
;                     const f32x4 za = (acc[ai][bj][m][0] * rr) * (w0a * p2a + w1a * p1a + w2a * c0a);
;                     const f32x4 zb = (acc[ai][bj][m][1] * rr) * (w0b * p2b + w1b * p1b + w2b * c0b);
;                     *(u32x4*)(Z + off) = pack8(za, zb);
	v_fmamk_f32 v102, v90, 0x3a000000, v205
	v_mul_f32_e32 v103, 0x4f800000, v102
	v_cmp_gt_f32_e32 vcc, s83, v102
	s_waitcnt vmcnt(2)
	v_lshlrev_b32_e32 v90, 16, v48
	s_waitcnt vmcnt(1)
	v_lshlrev_b32_e32 v94, 16, v52
	v_and_b32_e32 v95, 0xffff0000, v52
	v_lshlrev_b32_e32 v52, 16, v53
	v_and_b32_e32 v53, 0xffff0000, v53
	v_cndmask_b32_e32 v102, v102, v103, vcc
	v_lshlrev_b32_e32 v96, 16, v54
	s_waitcnt vmcnt(0)
	v_lshlrev_b32_e32 v98, 16, v56
	v_and_b32_e32 v99, 0xffff0000, v56
	v_lshlrev_b32_e32 v56, 16, v57
	v_and_b32_e32 v57, 0xffff0000, v57
	v_pk_mul_f32 v[98:99], v[84:85], v[98:99]
	v_pk_mul_f32 v[56:57], v[86:87], v[56:57]
	v_lshlrev_b32_e32 v100, 16, v58
	v_pk_fma_f32 v[52:53], v[78:79], v[52:53], v[56:57]
	v_pk_fma_f32 v[56:57], v[76:77], v[94:95], v[98:99]
	v_sqrt_f32_e32 v94, v102
	v_and_b32_e32 v101, 0xffff0000, v58
	v_lshlrev_b32_e32 v58, 16, v59
	v_and_b32_e32 v59, 0xffff0000, v59
	v_and_b32_e32 v97, 0xffff0000, v54
	v_lshlrev_b32_e32 v54, 16, v55
	v_and_b32_e32 v55, 0xffff0000, v55
	v_pk_mul_f32 v[100:101], v[80:81], v[100:101]
	v_pk_mul_f32 v[58:59], v[82:83], v[58:59]
	v_and_b32_e32 v91, 0xffff0000, v48
	v_lshlrev_b32_e32 v48, 16, v49
	v_and_b32_e32 v49, 0xffff0000, v49
	v_lshlrev_b32_e32 v92, 16, v50
	v_and_b32_e32 v93, 0xffff0000, v50
	v_pk_fma_f32 v[54:55], v[70:71], v[54:55], v[58:59]
	v_pk_fma_f32 v[58:59], v[68:69], v[96:97], v[100:101]
	v_pk_fma_f32 v[48:49], v[74:75], v[48:49], v[52:53]
	v_pk_fma_f32 v[52:53], v[64:65], v[92:93], v[58:59]
	v_add_u32_e32 v58, -1, v94
	v_pk_fma_f32 v[56:57], v[72:73], v[90:91], v[56:57]
	v_add_u32_e32 v59, 1, v94
	v_fma_f32 v90, -v58, v94, v102
	v_fma_f32 v91, -v59, v94, v102
	v_cmp_ge_f32_e64 s[0:1], 0, v90
	v_lshlrev_b32_e32 v50, 16, v51
	v_and_b32_e32 v51, 0xffff0000, v51
	v_cndmask_b32_e64 v58, v94, v58, s[0:1]
	v_cmp_lt_f32_e64 s[0:1], 0, v91
	v_pk_fma_f32 v[50:51], v[66:67], v[50:51], v[54:55]
	s_nop 0
	v_cndmask_b32_e64 v58, v58, v59, s[0:1]
	v_mul_f32_e32 v59, 0x37800000, v58
	v_cndmask_b32_e32 v58, v58, v59, vcc
	v_cmp_class_f32_e32 vcc, v102, v206
	s_nop 1
	v_cndmask_b32_e32 v58, v58, v102, vcc
	v_div_scale_f32 v59, s[0:1], v58, v58, 1.0
	v_rcp_f32_e32 v90, v59
	v_div_scale_f32 v54, vcc, 1.0, v58, 1.0
	v_fma_f32 v55, -v59, v90, 1.0
	v_fmac_f32_e32 v90, v55, v90
	v_mul_f32_e32 v55, v54, v90
	v_fma_f32 v91, -v59, v55, v54
	v_fmac_f32_e32 v55, v91, v90
	v_fma_f32 v54, -v59, v55, v54
	v_div_fmas_f32 v54, v54, v90, v55
	v_div_fixup_f32 v54, v54, v58, 1.0
	v_pk_mul_f32 v[46:47], v[46:47], v[54:55] op_sel_hi:[1,0]
	v_pk_mul_f32 v[40:41], v[40:41], v[54:55] op_sel_hi:[1,0]
	v_pk_mul_f32 v[42:43], v[42:43], v[54:55] op_sel_hi:[1,0]
	v_pk_mul_f32 v[44:45], v[44:45], v[54:55] op_sel_hi:[1,0]
	v_pk_mul_f32 v[46:47], v[46:47], v[48:49]
	v_pk_mul_f32 v[48:49], v[42:43], v[50:51]
	v_pk_mul_f32 v[42:43], v[40:41], v[52:53]
	v_pk_mul_f32 v[44:45], v[44:45], v[56:57]
	v_lshl_add_u64 v[56:57], s[14:15], 0, v[62:63]
	v_cvt_pk_bf16_f32 v40, v44, v45
	v_cvt_pk_bf16_f32 v41, v46, v47
	v_cvt_pk_bf16_f32 v42, v42, v43
	v_cvt_pk_bf16_f32 v43, v48, v49
	v_add_co_u32_e32 v48, vcc, s4, v88
	global_store_dwordx4 v[60:61], v[40:43], off
	s_nop 0
	v_addc_co_u32_e32 v49, vcc, -1, v89, vcc
	global_load_dword v58, v[140:141], off
	global_load_dwordx4 v[40:43], v[88:89], off
	global_load_dwordx4 v[44:47], v[88:89], off offset:-4096
	v_lshl_add_u64 v[52:53], v[142:143], 0, v[118:119]
	global_load_dwordx4 v[48:51], v[48:49], off
	v_lshl_add_u64 v[54:55], v[52:53], 1, s[12:13]
	s_waitcnt vmcnt(3)
	v_fmamk_f32 v94, v58, 0x3a000000, v205
	v_mul_f32_e32 v95, 0x4f800000, v94
	v_cmp_gt_f32_e32 vcc, s83, v94
	s_waitcnt vmcnt(1)
	v_lshlrev_b32_e32 v62, 16, v44
	s_waitcnt vmcnt(0)
	v_lshlrev_b32_e32 v90, 16, v48
	v_and_b32_e32 v91, 0xffff0000, v48
	v_lshlrev_b32_e32 v48, 16, v49
	v_and_b32_e32 v49, 0xffff0000, v49
	v_and_b32_e32 v63, 0xffff0000, v44
	v_lshlrev_b32_e32 v44, 16, v45
	v_and_b32_e32 v45, 0xffff0000, v45
	v_pk_mul_f32 v[90:91], v[84:85], v[90:91]
	v_pk_mul_f32 v[48:49], v[86:87], v[48:49]
	v_cndmask_b32_e32 v94, v94, v95, vcc
	v_pk_fma_f32 v[44:45], v[78:79], v[44:45], v[48:49]
	v_pk_fma_f32 v[48:49], v[76:77], v[62:63], v[90:91]
	v_sqrt_f32_e32 v62, v94
	v_lshlrev_b32_e32 v92, 16, v50
	v_and_b32_e32 v93, 0xffff0000, v50
	v_lshlrev_b32_e32 v50, 16, v51
	v_and_b32_e32 v51, 0xffff0000, v51
	v_lshlrev_b32_e32 v88, 16, v46
	v_and_b32_e32 v89, 0xffff0000, v46
	v_lshlrev_b32_e32 v46, 16, v47
	v_and_b32_e32 v47, 0xffff0000, v47
	v_pk_mul_f32 v[92:93], v[80:81], v[92:93]
	v_pk_mul_f32 v[50:51], v[82:83], v[50:51]
	v_lshlrev_b32_e32 v58, 16, v40
	v_and_b32_e32 v59, 0xffff0000, v40
	v_lshlrev_b32_e32 v40, 16, v41
	v_and_b32_e32 v41, 0xffff0000, v41
	v_lshlrev_b32_e32 v60, 16, v42
	v_and_b32_e32 v61, 0xffff0000, v42
	v_pk_fma_f32 v[46:47], v[70:71], v[46:47], v[50:51]
	v_pk_fma_f32 v[50:51], v[68:69], v[88:89], v[92:93]
	v_pk_fma_f32 v[40:41], v[74:75], v[40:41], v[44:45]
	v_pk_fma_f32 v[44:45], v[64:65], v[60:61], v[50:51]
	v_add_u32_e32 v50, -1, v62
	v_pk_fma_f32 v[48:49], v[72:73], v[58:59], v[48:49]
	v_add_u32_e32 v51, 1, v62
	v_fma_f32 v58, -v50, v62, v94
	v_fma_f32 v59, -v51, v62, v94
	v_cmp_ge_f32_e64 s[0:1], 0, v58
	v_lshlrev_b32_e32 v42, 16, v43
	v_and_b32_e32 v43, 0xffff0000, v43
	v_cndmask_b32_e64 v50, v62, v50, s[0:1]
	v_cmp_lt_f32_e64 s[0:1], 0, v59
	v_pk_fma_f32 v[42:43], v[66:67], v[42:43], v[46:47]
	s_nop 0
	v_cndmask_b32_e64 v50, v50, v51, s[0:1]
	v_mul_f32_e32 v51, 0x37800000, v50
	v_cndmask_b32_e32 v50, v50, v51, vcc
	v_cmp_class_f32_e32 vcc, v94, v206
	s_nop 1
	v_cndmask_b32_e32 v50, v50, v94, vcc
	v_div_scale_f32 v51, s[0:1], v50, v50, 1.0
	v_rcp_f32_e32 v58, v51
	v_div_scale_f32 v46, vcc, 1.0, v50, 1.0
	v_fma_f32 v47, -v51, v58, 1.0
	v_fmac_f32_e32 v58, v47, v58
	v_mul_f32_e32 v47, v46, v58
	v_fma_f32 v59, -v51, v47, v46
	v_fmac_f32_e32 v47, v59, v58
	v_fma_f32 v46, -v51, v47, v46
	v_div_fmas_f32 v46, v46, v58, v47
	v_div_fixup_f32 v46, v46, v50, 1.0
	v_pk_mul_f32 v[38:39], v[38:39], v[46:47] op_sel_hi:[1,0]
	v_pk_mul_f32 v[32:33], v[32:33], v[46:47] op_sel_hi:[1,0]
	v_pk_mul_f32 v[34:35], v[34:35], v[46:47] op_sel_hi:[1,0]
	v_pk_mul_f32 v[36:37], v[36:37], v[46:47] op_sel_hi:[1,0]
	v_pk_mul_f32 v[38:39], v[38:39], v[40:41]
	v_pk_mul_f32 v[40:41], v[34:35], v[42:43]
	v_pk_mul_f32 v[34:35], v[32:33], v[44:45]
	v_pk_mul_f32 v[36:37], v[36:37], v[48:49]
	s_nop 0
	v_cvt_pk_bf16_f32 v32, v36, v37
	v_cvt_pk_bf16_f32 v33, v38, v39
	v_cvt_pk_bf16_f32 v34, v34, v35
	v_cvt_pk_bf16_f32 v35, v40, v41
	global_store_dwordx4 v[56:57], v[32:35], off
	global_load_dword v56, v[188:189], off offset:512
	global_load_dwordx4 v[36:39], v[54:55], off
	s_and_saveexec_b64 s[0:1], s[6:7]
	s_xor_b64 s[0:1], exec, s[0:1]
	s_cbranch_execz .LBB0_536
;     __device__ __forceinline__ void operator()(const f32x4 (&acc)[2][2][4][2], const Unit& u, int wr, int wc, int fr, int fq) const {
;     ...
;                     else if (s == 1) { unpk(*(const u32x4*)(V + off - 2048), p1a, p1b); p2a = *(const f32x4*)(Vm + 15 * 2048 + ch0); p2b = *(const f32x4*)(Vm + 15 * 2048 + ch0 + 4); }
;                     else { p1a = *(const f32x4*)(Vm + 15 * 2048 + ch0); p1b = *(const f32x4*)(Vm + 15 * 2048 + ch0 + 4); p2a = *(const f32x4*)(Vm + 14 * 2048 + ch0); p2b = *(const f32x4*)(Vm + 14 * 2048 + ch0 + 4); }
	v_cmp_ne_u32_e32 vcc, 1, v158
	s_and_saveexec_b64 s[4:5], vcc
	s_xor_b64 s[4:5], exec, s[4:5]
	s_cbranch_execz .LBB0_533
	v_lshl_add_u64 v[40:41], s[20:21], 0, v[120:121]
	v_lshl_add_u64 v[48:49], s[22:23], 0, v[120:121]
	global_load_dwordx4 v[32:35], v[40:41], off offset:16
	s_nop 0
	global_load_dwordx4 v[40:43], v[40:41], off
	s_nop 0
	global_load_dwordx4 v[44:47], v[48:49], off offset:16
	s_nop 0
	global_load_dwordx4 v[48:51], v[48:49], off

; __device__ __forceinline__ u32x4 pack8(f32x4 a, f32x4 b) { u32x4 w; w.x = cvt_pk_bf16(a[0], a[1]); w.y = cvt_pk_bf16(a[2], a[3]); w.z = cvt_pk_bf16(b[0], b[1]); w.w = cvt_pk_bf16(b[2], b[3]); return w; }
; __device__ __forceinline__ float rs_of(const float* ss, int row) { return 1.0f / sqrtf(ss[row] * (1.0f / 2048.0f) + 1e-5f); }
;     __device__ __forceinline__ void operator()(const f32x4 (&acc)[2][2][4][2], const Unit& u, int wr, int wc, int fr, int fq) const {
;     ...
;                 for (int m = 0; m < 4; ++m) {
;                     const int row = row0 + ai * HALF + m * 16, s = row & 8191; const float rr = rs_of(ss, row);
;                     const size_t off = (size_t)row * 2048 + ch0;
;                     f32x4 c0a, c0b, p1a, p1b, p2a, p2b;
;                     unpk(*(const u32x4*)(V + off), c0a, c0b);
;                     if (s >= 2) { unpk(*(const u32x4*)(V + off - 2048), p1a, p1b); unpk(*(const u32x4*)(V + off - 4096), p2a, p2b); }
;                     else if (s == 1) { unpk(*(const u32x4*)(V + off - 2048), p1a, p1b); p2a = *(const f32x4*)(Vm + 15 * 2048 + ch0); p2b = *(const f32x4*)(Vm + 15 * 2048 + ch0 + 4); }
;                     else { p1a = *(const f32x4*)(Vm + 15 * 2048 + ch0); p1b = *(const f32x4*)(Vm + 15 * 2048 + ch0 + 4); p2a = *(const f32x4*)(Vm + 14 * 2048 + ch0); p2b = *(const f32x4*)(Vm + 14 * 2048 + ch0 + 4); }
;                     const f32x4 za = (acc[ai][bj][m][0] * rr) * (w0a * p2a + w1a * p1a + w2a * c0a);
;                     const f32x4 zb = (acc[ai][bj][m][1] * rr) * (w0b * p2b + w1b * p1b + w2b * c0b);
;                     *(u32x4*)(Z + off) = pack8(za, zb);
;                     if (m & 1) asm volatile("" ::: "memory");
;                 }
.LBB0_538:
	s_or_b64 exec, exec, s[0:1]
	s_waitcnt vmcnt(0)
	v_lshlrev_b32_e32 v54, 16, v38
	v_and_b32_e32 v55, 0xffff0000, v38
	v_fmamk_f32 v38, v56, 0x3a000000, v205
	v_mul_f32_e32 v56, 0x4f800000, v38
	v_cmp_gt_f32_e32 vcc, s83, v38
	v_pk_mul_f32 v[40:41], v[76:77], v[40:41]
	v_pk_mul_f32 v[42:43], v[78:79], v[42:43]
	v_cndmask_b32_e32 v57, v38, v56, vcc
	v_sqrt_f32_e32 v58, v57
	v_lshlrev_b32_e32 v56, 16, v36
	v_pk_fma_f32 v[40:41], v[84:85], v[48:49], v[40:41]
	v_pk_mul_f32 v[34:35], v[70:71], v[34:35]
	v_add_u32_e32 v59, -1, v58
	v_fma_f32 v60, -v59, v58, v57
	v_cmp_ge_f32_e64 s[0:1], 0, v60
	v_add_u32_e32 v60, 1, v58
	v_pk_mul_f32 v[32:33], v[68:69], v[32:33]
	v_cndmask_b32_e64 v59, v58, v59, s[0:1]
	v_fma_f32 v58, -v60, v58, v57
	v_cmp_lt_f32_e64 s[0:1], 0, v58
	v_lshlrev_b32_e32 v38, 16, v39
	v_and_b32_e32 v39, 0xffff0000, v39
	v_cndmask_b32_e64 v58, v59, v60, s[0:1]
	v_mul_f32_e32 v59, 0x37800000, v58
	v_cndmask_b32_e32 v58, v58, v59, vcc
	v_cmp_class_f32_e32 vcc, v57, v206
	v_pk_fma_f32 v[42:43], v[86:87], v[50:51], v[42:43]
	v_pk_fma_f32 v[34:35], v[82:83], v[46:47], v[34:35]
	v_cndmask_b32_e32 v58, v58, v57, vcc
	v_div_scale_f32 v59, s[0:1], v58, v58, 1.0
	v_rcp_f32_e32 v60, v59
	v_and_b32_e32 v57, 0xffff0000, v36
	v_lshlrev_b32_e32 v36, 16, v37
	v_and_b32_e32 v37, 0xffff0000, v37
	v_fma_f32 v61, -v59, v60, 1.0
	v_fmac_f32_e32 v60, v61, v60
	v_div_scale_f32 v61, vcc, 1.0, v58, 1.0
	v_mul_f32_e32 v62, v61, v60
	v_fma_f32 v63, -v59, v62, v61
	v_fmac_f32_e32 v62, v63, v60
	v_fma_f32 v59, -v59, v62, v61
	v_div_fmas_f32 v59, v59, v60, v62
	v_div_fixup_f32 v58, v59, v58, 1.0
	v_pk_mul_f32 v[28:29], v[28:29], v[58:59] op_sel_hi:[1,0]
	v_pk_fma_f32 v[40:41], v[72:73], v[56:57], v[40:41]
	v_pk_fma_f32 v[32:33], v[80:81], v[44:45], v[32:33]
	v_pk_mul_f32 v[30:31], v[30:31], v[58:59] op_sel_hi:[1,0]
	v_pk_fma_f32 v[36:37], v[74:75], v[36:37], v[42:43]
	v_pk_mul_f32 v[28:29], v[28:29], v[40:41]
	v_pk_mul_f32 v[24:25], v[24:25], v[58:59] op_sel_hi:[1,0]
	v_pk_mul_f32 v[26:27], v[26:27], v[58:59] op_sel_hi:[1,0]
	v_pk_fma_f32 v[34:35], v[66:67], v[38:39], v[34:35]
	v_pk_fma_f32 v[32:33], v[64:65], v[54:55], v[32:33]
	v_pk_mul_f32 v[30:31], v[30:31], v[36:37]
	v_pk_mul_f32 v[34:35], v[26:27], v[34:35]
	v_pk_mul_f32 v[26:27], v[24:25], v[32:33]
	v_cvt_pk_bf16_f32 v24, v28, v29
	v_cvt_pk_bf16_f32 v25, v30, v31
	v_lshl_add_u64 v[28:29], v[52:53], 1, s[14:15]
	v_cvt_pk_bf16_f32 v26, v26, v27
	v_cvt_pk_bf16_f32 v27, v34, v35
	global_store_dwordx4 v[28:29], v[24:27], off
	global_load_dword v38, v[188:189], off offset:576
	s_movk_i32 s4, 0xe000
	v_lshl_add_u64 v[24:25], v[112:113], 0, v[118:119]
	v_lshlrev_b64 v[36:37], 1, v[24:25]
	v_lshl_add_u64 v[32:33], s[12:13], 0, v[36:37]
	global_load_dwordx4 v[24:27], v[32:33], off
	global_load_dwordx4 v[28:31], v[32:33], off offset:-4096
	v_add_co_u32_e32 v32, vcc, s4, v32
	s_nop 1
	v_addc_co_u32_e32 v33, vcc, -1, v33, vcc
	global_load_dwordx4 v[32:35], v[32:33], off
	s_waitcnt vmcnt(3)
	v_fmamk_f32 v50, v38, 0x3a000000, v205
	v_mul_f32_e32 v51, 0x4f800000, v50
	v_cmp_gt_f32_e32 vcc, s83, v50
	s_waitcnt vmcnt(1)
	v_lshlrev_b32_e32 v42, 16, v28
	v_and_b32_e32 v43, 0xffff0000, v28
	v_cndmask_b32_e32 v50, v50, v51, vcc
	v_sqrt_f32_e32 v51, v50
	v_lshlrev_b32_e32 v28, 16, v29
	v_and_b32_e32 v29, 0xffff0000, v29
	v_lshlrev_b32_e32 v38, 16, v24
	v_and_b32_e32 v39, 0xffff0000, v24
	v_lshlrev_b32_e32 v24, 16, v25
	v_and_b32_e32 v25, 0xffff0000, v25
	v_lshlrev_b32_e32 v44, 16, v30
	v_and_b32_e32 v45, 0xffff0000, v30
	v_lshlrev_b32_e32 v30, 16, v31
	v_and_b32_e32 v31, 0xffff0000, v31
	v_lshlrev_b32_e32 v40, 16, v26
	v_and_b32_e32 v41, 0xffff0000, v26
	v_lshlrev_b32_e32 v26, 16, v27
	v_and_b32_e32 v27, 0xffff0000, v27
	s_waitcnt vmcnt(0)
	v_lshlrev_b32_e32 v46, 16, v32
	v_and_b32_e32 v47, 0xffff0000, v32
	v_lshlrev_b32_e32 v32, 16, v33
	v_and_b32_e32 v33, 0xffff0000, v33
	v_pk_mul_f32 v[46:47], v[84:85], v[46:47]
	v_pk_mul_f32 v[32:33], v[86:87], v[32:33]
	v_lshlrev_b32_e32 v48, 16, v34
	v_pk_fma_f32 v[28:29], v[78:79], v[28:29], v[32:33]
	v_pk_fma_f32 v[32:33], v[76:77], v[42:43], v[46:47]
	v_pk_fma_f32 v[24:25], v[74:75], v[24:25], v[28:29]
	v_pk_fma_f32 v[32:33], v[72:73], v[38:39], v[32:33]
	v_add_u32_e32 v38, -1, v51
	v_add_u32_e32 v39, 1, v51
	v_fma_f32 v42, -v38, v51, v50
	v_fma_f32 v43, -v39, v51, v50
	v_cmp_ge_f32_e64 s[0:1], 0, v42
	v_and_b32_e32 v49, 0xffff0000, v34
	v_lshlrev_b32_e32 v34, 16, v35
	v_cndmask_b32_e64 v38, v51, v38, s[0:1]
	v_cmp_lt_f32_e64 s[0:1], 0, v43
	v_and_b32_e32 v35, 0xffff0000, v35
	s_nop 0
	v_cndmask_b32_e64 v38, v38, v39, s[0:1]
	v_mul_f32_e32 v39, 0x37800000, v38
	v_cndmask_b32_e32 v38, v38, v39, vcc
	v_cmp_class_f32_e32 vcc, v50, v206
	s_nop 1
	v_cndmask_b32_e32 v38, v38, v50, vcc
	v_div_scale_f32 v39, s[0:1], v38, v38, 1.0
	v_rcp_f32_e32 v42, v39
	v_div_scale_f32 v28, vcc, 1.0, v38, 1.0
	v_fma_f32 v29, -v39, v42, 1.0
	v_fmac_f32_e32 v42, v29, v42
	v_mul_f32_e32 v29, v28, v42
	v_fma_f32 v43, -v39, v29, v28
	v_fmac_f32_e32 v29, v43, v42
	v_fma_f32 v28, -v39, v29, v28
	v_div_fmas_f32 v28, v28, v42, v29
	v_div_fixup_f32 v28, v28, v38, 1.0
	v_pk_mul_f32 v[22:23], v[22:23], v[28:29] op_sel_hi:[1,0]
	v_pk_mul_f32 v[20:21], v[20:21], v[28:29] op_sel_hi:[1,0]
	v_pk_mul_f32 v[22:23], v[22:23], v[24:25]
	v_pk_mul_f32 v[16:17], v[16:17], v[28:29] op_sel_hi:[1,0]
	v_pk_mul_f32 v[18:19], v[18:19], v[28:29] op_sel_hi:[1,0]
	v_pk_mul_f32 v[24:25], v[80:81], v[48:49]
	v_pk_mul_f32 v[28:29], v[82:83], v[34:35]
	v_pk_fma_f32 v[24:25], v[68:69], v[44:45], v[24:25]
	v_pk_fma_f32 v[28:29], v[70:71], v[30:31], v[28:29]
	v_pk_mul_f32 v[20:21], v[20:21], v[32:33]
	v_pk_fma_f32 v[24:25], v[64:65], v[40:41], v[24:25]
	v_pk_fma_f32 v[26:27], v[66:67], v[26:27], v[28:29]
	v_lshl_add_u64 v[30:31], v[116:117], 0, v[118:119]
	v_pk_mul_f32 v[26:27], v[18:19], v[26:27]
	v_pk_mul_f32 v[18:19], v[16:17], v[24:25]
	v_cvt_pk_bf16_f32 v16, v20, v21
	v_cvt_pk_bf16_f32 v17, v22, v23
	v_lshl_add_u64 v[20:21], s[14:15], 0, v[36:37]
	v_cvt_pk_bf16_f32 v18, v18, v19
	v_cvt_pk_bf16_f32 v19, v26, v27
	global_store_dwordx4 v[20:21], v[16:19], off
	global_load_dword v34, v[188:189], off offset:640
	v_lshlrev_b64 v[30:31], 1, v[30:31]
	v_lshl_add_u64 v[16:17], v[114:115], 0, v[118:119]
	v_lshlrev_b64 v[28:29], 1, v[16:17]
	v_lshl_add_u64 v[24:25], s[12:13], 0, v[28:29]
	global_load_dwordx4 v[16:19], v[24:25], off
	global_load_dwordx4 v[20:23], v[24:25], off offset:-4096
	v_add_co_u32_e32 v24, vcc, s4, v24
	v_lshl_add_u64 v[32:33], s[12:13], 0, v[30:31]
	s_nop 0
	v_addc_co_u32_e32 v25, vcc, -1, v25, vcc
	global_load_dwordx4 v[24:27], v[24:25], off
	v_lshl_add_u64 v[28:29], s[14:15], 0, v[28:29]
	s_waitcnt vmcnt(3)
; __device__ __forceinline__ u32x4 pack8(f32x4 a, f32x4 b) { u32x4 w; w.x = cvt_pk_bf16(a[0], a[1]); w.y = cvt_pk_bf16(a[2], a[3]); w.z = cvt_pk_bf16(b[0], b[1]); w.w = cvt_pk_bf16(b[2], b[3]); return w; }
; __device__ __forceinline__ float rs_of(const float* ss, int row) { return 1.0f / sqrtf(ss[row] * (1.0f / 2048.0f) + 1e-5f); }
;     __device__ __forceinline__ void operator()(const f32x4 (&acc)[2][2][4][2], const Unit& u, int wr, int wc, int fr, int fq) const {
;     ...
;                 for (int m = 0; m < 4; ++m) {
;                     const int row = row0 + ai * HALF + m * 16, s = row & 8191; const float rr = rs_of(ss, row);
;                     const size_t off = (size_t)row * 2048 + ch0;
;                     f32x4 c0a, c0b, p1a, p1b, p2a, p2b;
;                     unpk(*(const u32x4*)(V + off), c0a, c0b);
;                     if (s >= 2) { unpk(*(const u32x4*)(V + off - 2048), p1a, p1b); unpk(*(const u32x4*)(V + off - 4096), p2a, p2b); }
;                     else if (s == 1) { unpk(*(const u32x4*)(V + off - 2048), p1a, p1b); p2a = *(const f32x4*)(Vm + 15 * 2048 + ch0); p2b = *(const f32x4*)(Vm + 15 * 2048 + ch0 + 4); }
;                     else { p1a = *(const f32x4*)(Vm + 15 * 2048 + ch0); p1b = *(const f32x4*)(Vm + 15 * 2048 + ch0 + 4); p2a = *(const f32x4*)(Vm + 14 * 2048 + ch0); p2b = *(const f32x4*)(Vm + 14 * 2048 + ch0 + 4); }
;                     const f32x4 za = (acc[ai][bj][m][0] * rr) * (w0a * p2a + w1a * p1a + w2a * c0a);
;                     const f32x4 zb = (acc[ai][bj][m][1] * rr) * (w0b * p2b + w1b * p1b + w2b * c0b);
;                     *(u32x4*)(Z + off) = pack8(za, zb);
;                     if (m & 1) asm volatile("" ::: "memory");
;                 }
	v_fmamk_f32 v46, v34, 0x3a000000, v205
	v_mul_f32_e32 v47, 0x4f800000, v46
	v_cmp_gt_f32_e32 vcc, s83, v46
	s_waitcnt vmcnt(2)
	v_lshlrev_b32_e32 v34, 16, v16
	s_waitcnt vmcnt(1)
	v_lshlrev_b32_e32 v38, 16, v20
	v_and_b32_e32 v39, 0xffff0000, v20
	v_lshlrev_b32_e32 v20, 16, v21
	v_and_b32_e32 v21, 0xffff0000, v21
	v_cndmask_b32_e32 v46, v46, v47, vcc
	v_lshlrev_b32_e32 v40, 16, v22
	s_waitcnt vmcnt(0)
	v_lshlrev_b32_e32 v42, 16, v24
	v_and_b32_e32 v43, 0xffff0000, v24
	v_lshlrev_b32_e32 v24, 16, v25
	v_and_b32_e32 v25, 0xffff0000, v25
	v_pk_mul_f32 v[42:43], v[84:85], v[42:43]
	v_pk_mul_f32 v[24:25], v[86:87], v[24:25]
	v_lshlrev_b32_e32 v44, 16, v26
	v_pk_fma_f32 v[20:21], v[78:79], v[20:21], v[24:25]
	v_pk_fma_f32 v[24:25], v[76:77], v[38:39], v[42:43]
	v_sqrt_f32_e32 v38, v46
	v_and_b32_e32 v45, 0xffff0000, v26
	v_lshlrev_b32_e32 v26, 16, v27
	v_and_b32_e32 v27, 0xffff0000, v27
	v_and_b32_e32 v41, 0xffff0000, v22
	v_lshlrev_b32_e32 v22, 16, v23
	v_and_b32_e32 v23, 0xffff0000, v23
	v_pk_mul_f32 v[44:45], v[80:81], v[44:45]
	v_pk_mul_f32 v[26:27], v[82:83], v[26:27]
	v_and_b32_e32 v35, 0xffff0000, v16
	v_lshlrev_b32_e32 v16, 16, v17
	v_and_b32_e32 v17, 0xffff0000, v17
	v_lshlrev_b32_e32 v36, 16, v18
	v_and_b32_e32 v37, 0xffff0000, v18
	v_pk_fma_f32 v[22:23], v[70:71], v[22:23], v[26:27]
	v_pk_fma_f32 v[26:27], v[68:69], v[40:41], v[44:45]
	v_pk_fma_f32 v[16:17], v[74:75], v[16:17], v[20:21]
	v_pk_fma_f32 v[20:21], v[64:65], v[36:37], v[26:27]
	v_add_u32_e32 v26, -1, v38
	v_pk_fma_f32 v[24:25], v[72:73], v[34:35], v[24:25]
	v_add_u32_e32 v27, 1, v38
	v_fma_f32 v34, -v26, v38, v46
	v_fma_f32 v35, -v27, v38, v46
	v_cmp_ge_f32_e64 s[0:1], 0, v34
	v_lshlrev_b32_e32 v18, 16, v19
	v_and_b32_e32 v19, 0xffff0000, v19
	v_cndmask_b32_e64 v26, v38, v26, s[0:1]
	v_cmp_lt_f32_e64 s[0:1], 0, v35
	v_pk_fma_f32 v[18:19], v[66:67], v[18:19], v[22:23]
	s_nop 0
	v_cndmask_b32_e64 v26, v26, v27, s[0:1]
	v_mul_f32_e32 v27, 0x37800000, v26
	v_cndmask_b32_e32 v26, v26, v27, vcc
	v_cmp_class_f32_e32 vcc, v46, v206
	s_nop 1
	v_cndmask_b32_e32 v26, v26, v46, vcc
	v_div_scale_f32 v27, s[0:1], v26, v26, 1.0
	v_rcp_f32_e32 v34, v27
	v_div_scale_f32 v22, vcc, 1.0, v26, 1.0
	v_fma_f32 v23, -v27, v34, 1.0
	v_fmac_f32_e32 v34, v23, v34
	v_mul_f32_e32 v23, v22, v34
	v_fma_f32 v35, -v27, v23, v22
	v_fmac_f32_e32 v23, v35, v34
	v_fma_f32 v22, -v27, v23, v22
	v_div_fmas_f32 v22, v22, v34, v23
	v_div_fixup_f32 v22, v22, v26, 1.0
	v_pk_mul_f32 v[14:15], v[14:15], v[22:23] op_sel_hi:[1,0]
	v_pk_mul_f32 v[8:9], v[8:9], v[22:23] op_sel_hi:[1,0]
	v_pk_mul_f32 v[10:11], v[10:11], v[22:23] op_sel_hi:[1,0]
	v_pk_mul_f32 v[12:13], v[12:13], v[22:23] op_sel_hi:[1,0]
	v_pk_mul_f32 v[14:15], v[14:15], v[16:17]
	v_pk_mul_f32 v[16:17], v[10:11], v[18:19]
	v_pk_mul_f32 v[10:11], v[8:9], v[20:21]
	v_pk_mul_f32 v[12:13], v[12:13], v[24:25]
	v_lshl_add_u64 v[20:21], s[14:15], 0, v[30:31]
	v_cvt_pk_bf16_f32 v8, v12, v13
	v_cvt_pk_bf16_f32 v9, v14, v15
	v_cvt_pk_bf16_f32 v10, v10, v11
	v_cvt_pk_bf16_f32 v11, v16, v17
	v_add_co_u32_e32 v16, vcc, s4, v32
	global_store_dwordx4 v[28:29], v[8:11], off
	s_nop 0
	v_addc_co_u32_e32 v17, vcc, -1, v33, vcc
	global_load_dword v22, v[188:189], off offset:704
	global_load_dwordx4 v[8:11], v[32:33], off
	global_load_dwordx4 v[12:15], v[32:33], off offset:-4096
	global_load_dwordx4 v[16:19], v[16:17], off
	s_waitcnt vmcnt(3)
	v_fmamk_f32 v34, v22, 0x3a000000, v205
	v_mul_f32_e32 v35, 0x4f800000, v34
	v_cmp_gt_f32_e32 vcc, s83, v34
	s_waitcnt vmcnt(1)
	v_lshlrev_b32_e32 v26, 16, v12
	v_and_b32_e32 v27, 0xffff0000, v12
	v_lshlrev_b32_e32 v12, 16, v13
	v_and_b32_e32 v13, 0xffff0000, v13
	v_cndmask_b32_e32 v34, v34, v35, vcc
	v_lshlrev_b32_e32 v28, 16, v14
	v_and_b32_e32 v29, 0xffff0000, v14
	v_lshlrev_b32_e32 v14, 16, v15
	v_and_b32_e32 v15, 0xffff0000, v15
	v_lshlrev_b32_e32 v22, 16, v8
	v_and_b32_e32 v23, 0xffff0000, v8
	v_lshlrev_b32_e32 v8, 16, v9
	v_and_b32_e32 v9, 0xffff0000, v9
	v_lshlrev_b32_e32 v24, 16, v10
	v_and_b32_e32 v25, 0xffff0000, v10
	v_lshlrev_b32_e32 v10, 16, v11
	v_and_b32_e32 v11, 0xffff0000, v11
	s_waitcnt vmcnt(0)
	v_lshlrev_b32_e32 v30, 16, v16
	v_and_b32_e32 v31, 0xffff0000, v16
	v_lshlrev_b32_e32 v16, 16, v17
	v_and_b32_e32 v17, 0xffff0000, v17
	v_pk_mul_f32 v[30:31], v[84:85], v[30:31]
	v_pk_mul_f32 v[16:17], v[86:87], v[16:17]
	v_lshlrev_b32_e32 v32, 16, v18
	v_pk_fma_f32 v[12:13], v[78:79], v[12:13], v[16:17]
	v_pk_fma_f32 v[16:17], v[76:77], v[26:27], v[30:31]
	v_sqrt_f32_e32 v26, v34
	v_and_b32_e32 v33, 0xffff0000, v18
	v_lshlrev_b32_e32 v18, 16, v19
	v_and_b32_e32 v19, 0xffff0000, v19
	v_pk_mul_f32 v[32:33], v[80:81], v[32:33]
	v_pk_mul_f32 v[18:19], v[82:83], v[18:19]
	v_pk_fma_f32 v[8:9], v[74:75], v[8:9], v[12:13]
	v_pk_fma_f32 v[14:15], v[70:71], v[14:15], v[18:19]
	v_pk_fma_f32 v[18:19], v[68:69], v[28:29], v[32:33]
	v_pk_fma_f32 v[16:17], v[72:73], v[22:23], v[16:17]
	v_pk_fma_f32 v[12:13], v[64:65], v[24:25], v[18:19]
	v_add_u32_e32 v18, -1, v26
	v_add_u32_e32 v19, 1, v26
	v_fma_f32 v22, -v18, v26, v34
	v_fma_f32 v23, -v19, v26, v34
	v_cmp_ge_f32_e64 s[0:1], 0, v22
	v_pk_fma_f32 v[10:11], v[66:67], v[10:11], v[14:15]
	s_nop 0
	v_cndmask_b32_e64 v18, v26, v18, s[0:1]
	v_cmp_lt_f32_e64 s[0:1], 0, v23
	s_nop 1
	v_cndmask_b32_e64 v18, v18, v19, s[0:1]
	v_mul_f32_e32 v19, 0x37800000, v18
	v_cndmask_b32_e32 v18, v18, v19, vcc
	v_cmp_class_f32_e32 vcc, v34, v206
	s_nop 1
	v_cndmask_b32_e32 v18, v18, v34, vcc
	v_div_scale_f32 v19, s[0:1], v18, v18, 1.0
	v_rcp_f32_e32 v22, v19
	v_div_scale_f32 v14, vcc, 1.0, v18, 1.0
	s_mov_b64 s[0:1], -1
	v_fma_f32 v15, -v19, v22, 1.0
	v_fmac_f32_e32 v22, v15, v22
	v_mul_f32_e32 v15, v14, v22
	v_fma_f32 v23, -v19, v15, v14
	v_fmac_f32_e32 v15, v23, v22
	v_fma_f32 v14, -v19, v15, v14
	v_div_fmas_f32 v14, v14, v22, v15
	v_div_fixup_f32 v14, v14, v18, 1.0
	v_pk_mul_f32 v[6:7], v[6:7], v[14:15] op_sel_hi:[1,0]
	v_pk_mul_f32 v[0:1], v[0:1], v[14:15] op_sel_hi:[1,0]
	v_pk_mul_f32 v[2:3], v[2:3], v[14:15] op_sel_hi:[1,0]
	v_pk_mul_f32 v[4:5], v[4:5], v[14:15] op_sel_hi:[1,0]
	v_pk_mul_f32 v[6:7], v[6:7], v[8:9]
	v_pk_mul_f32 v[8:9], v[2:3], v[10:11]
	v_pk_mul_f32 v[2:3], v[0:1], v[12:13]
	v_pk_mul_f32 v[4:5], v[4:5], v[16:17]
	s_andn2_b64 vcc, exec, s[2:3]
	v_cvt_pk_bf16_f32 v0, v4, v5
	v_cvt_pk_bf16_f32 v1, v6, v7
	v_cvt_pk_bf16_f32 v2, v2, v3
	v_cvt_pk_bf16_f32 v3, v8, v9
	global_store_dwordx4 v[20:21], v[0:3], off
	s_cbranch_vccnz .LBB0_491
	s_andn2_b64 vcc, exec, s[10:11]
	s_cbranch_vccnz .LBB0_490
	s_barrier
	s_branch .LBB0_490
